# scan step loops: per-lane state as row pairs (25 VALU/step instead of 29), on top of M1
# speedup vs baseline: 1.0091x; 1.0091x over previous
.LBB0_415:
	v_swap_b32 v17, v12
	v_swap_b32 v19, v14
	s_waitcnt lgkmcnt(0)
	v_pk_mul_f32 v[132:133], v[16:17], v[32:33] op_sel_hi:[1,0]
	v_pk_fma_f32 v[132:133], v[12:13], v[32:33], v[132:133] op_sel:[0,1,0]
	v_pk_fma_f32 v[132:133], v[18:19], v[34:35], v[132:133] op_sel_hi:[1,0,1]
	v_pk_fma_f32 v[132:133], v[14:15], v[34:35], v[132:133] op_sel:[0,1,0]
	v_pk_fma_f32 v[16:17], v[28:29], v[90:91], v[16:17] op_sel_hi:[0,1,1]
	v_pk_fma_f32 v[12:13], v[28:29], v[90:91], v[12:13] op_sel:[1,0,0]
	v_add_f32_dpp v132, v132, v132 quad_perm:[1,0,3,2] row_mask:0xf bank_mask:0xf bound_ctrl:1
	v_add_f32_dpp v133, v133, v133 quad_perm:[1,0,3,2] row_mask:0xf bank_mask:0xf bound_ctrl:1
	v_pk_fma_f32 v[18:19], v[30:31], v[90:91], v[18:19] op_sel_hi:[0,1,1]
	v_add_f32_dpp v132, v132, v132 quad_perm:[2,3,0,1] row_mask:0xf bank_mask:0xf bound_ctrl:1
	v_add_f32_dpp v133, v133, v133 quad_perm:[2,3,0,1] row_mask:0xf bank_mask:0xf bound_ctrl:1
	v_pk_fma_f32 v[14:15], v[30:31], v[90:91], v[14:15] op_sel:[1,0,0]
	v_add_f32_dpp v132, v132, v132 row_half_mirror row_mask:0xf bank_mask:0xf bound_ctrl:1
	v_add_f32_dpp v133, v133, v133 row_half_mirror row_mask:0xf bank_mask:0xf bound_ctrl:1
	ds_read_b128 v[94:97], v42 offset:12288
	ds_read_b128 v[116:119], v42 offset:16384
	ds_read_b128 v[120:123], v42 offset:8192
	ds_read_b128 v[124:127], v42
	ds_read_b64 v[130:131], v92
	v_add_f32_dpp v132, v132, v132 row_mirror row_mask:0xf bank_mask:0xf bound_ctrl:1
	v_add_f32_dpp v133, v133, v133 row_mirror row_mask:0xf bank_mask:0xf bound_ctrl:1
	v_pk_fma_f32 v[16:17], v[24:25], v[132:133], v[16:17] op_sel_hi:[0,1,1]
	v_pk_fma_f32 v[12:13], v[24:25], v[132:133], v[12:13] op_sel:[1,0,0]
	v_pk_fma_f32 v[18:19], v[26:27], v[132:133], v[18:19] op_sel_hi:[0,1,1]
	v_pk_fma_f32 v[14:15], v[26:27], v[132:133], v[14:15] op_sel:[1,0,0]
	s_waitcnt lgkmcnt(4)
	v_pk_mul_f32 v[132:133], v[16:17], v[94:95] op_sel_hi:[1,0]
	v_pk_mul_f32 v[24:25], v[16:17], v[20:21] op_sel_hi:[1,0]
	v_pk_fma_f32 v[132:133], v[12:13], v[94:95], v[132:133] op_sel:[0,1,0]
	v_pk_fma_f32 v[24:25], v[12:13], v[20:21], v[24:25] op_sel:[0,1,0]
	v_pk_fma_f32 v[132:133], v[18:19], v[96:97], v[132:133] op_sel_hi:[1,0,1]
	v_pk_fma_f32 v[24:25], v[18:19], v[22:23], v[24:25] op_sel_hi:[1,0,1]
	v_pk_fma_f32 v[132:133], v[14:15], v[96:97], v[132:133] op_sel:[0,1,0]
	v_pk_fma_f32 v[24:25], v[14:15], v[22:23], v[24:25] op_sel:[0,1,0]
	v_cvt_pk_f16_f32 v24, v24, v25
	v_add_f32_dpp v132, v132, v132 quad_perm:[1,0,3,2] row_mask:0xf bank_mask:0xf bound_ctrl:1
	v_add_f32_dpp v133, v133, v133 quad_perm:[1,0,3,2] row_mask:0xf bank_mask:0xf bound_ctrl:1
	ds_write_b32 v93, v24
	ds_read_b128 v[32:35], v114 offset:12800
	ds_read_b128 v[24:27], v114 offset:16896
	ds_read_b128 v[28:31], v114 offset:8704
	ds_read_b128 v[20:23], v114 offset:512
	s_waitcnt lgkmcnt(5)
	v_pk_fma_f32 v[16:17], v[120:121], v[130:131], v[16:17] op_sel_hi:[0,1,1]
	v_add_f32_dpp v132, v132, v132 quad_perm:[2,3,0,1] row_mask:0xf bank_mask:0xf bound_ctrl:1
	v_add_f32_dpp v133, v133, v133 quad_perm:[2,3,0,1] row_mask:0xf bank_mask:0xf bound_ctrl:1
	v_pk_fma_f32 v[12:13], v[120:121], v[130:131], v[12:13] op_sel:[1,0,0]
	v_add_f32_dpp v132, v132, v132 row_half_mirror row_mask:0xf bank_mask:0xf bound_ctrl:1
	v_add_f32_dpp v133, v133, v133 row_half_mirror row_mask:0xf bank_mask:0xf bound_ctrl:1
	v_pk_fma_f32 v[18:19], v[122:123], v[130:131], v[18:19] op_sel_hi:[0,1,1]
	v_pk_fma_f32 v[14:15], v[122:123], v[130:131], v[14:15] op_sel:[1,0,0]
	v_add_f32_dpp v132, v132, v132 row_mirror row_mask:0xf bank_mask:0xf bound_ctrl:1
	v_add_f32_dpp v133, v133, v133 row_mirror row_mask:0xf bank_mask:0xf bound_ctrl:1
	v_pk_fma_f32 v[16:17], v[116:117], v[132:133], v[16:17] op_sel_hi:[0,1,1]
	v_pk_fma_f32 v[12:13], v[116:117], v[132:133], v[12:13] op_sel:[1,0,0]
	v_pk_fma_f32 v[18:19], v[118:119], v[132:133], v[18:19] op_sel_hi:[0,1,1]
	v_pk_fma_f32 v[14:15], v[118:119], v[132:133], v[14:15] op_sel:[1,0,0]
	ds_read_b64 v[90:91], v115 offset:20736
	v_pk_mul_f32 v[94:95], v[16:17], v[124:125] op_sel_hi:[1,0]
	v_pk_fma_f32 v[94:95], v[12:13], v[124:125], v[94:95] op_sel:[0,1,0]
	v_pk_fma_f32 v[94:95], v[18:19], v[126:127], v[94:95] op_sel_hi:[1,0,1]
	v_pk_fma_f32 v[94:95], v[14:15], v[126:127], v[94:95] op_sel:[0,1,0]
	v_cvt_pk_f16_f32 v94, v94, v95
	ds_write_b32 v93, v94 offset:1024
	s_waitcnt lgkmcnt(0)
	v_pk_mul_f32 v[132:133], v[16:17], v[32:33] op_sel_hi:[1,0]
	v_pk_fma_f32 v[132:133], v[12:13], v[32:33], v[132:133] op_sel:[0,1,0]
	v_pk_fma_f32 v[132:133], v[18:19], v[34:35], v[132:133] op_sel_hi:[1,0,1]
	v_pk_fma_f32 v[132:133], v[14:15], v[34:35], v[132:133] op_sel:[0,1,0]
	v_pk_fma_f32 v[16:17], v[28:29], v[90:91], v[16:17] op_sel_hi:[0,1,1]
	v_pk_fma_f32 v[12:13], v[28:29], v[90:91], v[12:13] op_sel:[1,0,0]
	v_add_f32_dpp v132, v132, v132 quad_perm:[1,0,3,2] row_mask:0xf bank_mask:0xf bound_ctrl:1
	v_add_f32_dpp v133, v133, v133 quad_perm:[1,0,3,2] row_mask:0xf bank_mask:0xf bound_ctrl:1
	v_pk_fma_f32 v[18:19], v[30:31], v[90:91], v[18:19] op_sel_hi:[0,1,1]
	v_add_f32_dpp v132, v132, v132 quad_perm:[2,3,0,1] row_mask:0xf bank_mask:0xf bound_ctrl:1
	v_add_f32_dpp v133, v133, v133 quad_perm:[2,3,0,1] row_mask:0xf bank_mask:0xf bound_ctrl:1
	v_pk_fma_f32 v[14:15], v[30:31], v[90:91], v[14:15] op_sel:[1,0,0]
	v_add_f32_dpp v132, v132, v132 row_half_mirror row_mask:0xf bank_mask:0xf bound_ctrl:1
	v_add_f32_dpp v133, v133, v133 row_half_mirror row_mask:0xf bank_mask:0xf bound_ctrl:1
	ds_read_b128 v[94:97], v42 offset:12800
	ds_read_b128 v[116:119], v42 offset:16896
	ds_read_b128 v[120:123], v42 offset:8704
	ds_read_b128 v[124:127], v42 offset:512
	ds_read_b64 v[130:131], v92 offset:256
	v_add_f32_dpp v132, v132, v132 row_mirror row_mask:0xf bank_mask:0xf bound_ctrl:1
	v_add_f32_dpp v133, v133, v133 row_mirror row_mask:0xf bank_mask:0xf bound_ctrl:1
	v_pk_fma_f32 v[16:17], v[24:25], v[132:133], v[16:17] op_sel_hi:[0,1,1]
	v_pk_fma_f32 v[12:13], v[24:25], v[132:133], v[12:13] op_sel:[1,0,0]
	v_pk_fma_f32 v[18:19], v[26:27], v[132:133], v[18:19] op_sel_hi:[0,1,1]
	v_pk_fma_f32 v[14:15], v[26:27], v[132:133], v[14:15] op_sel:[1,0,0]
	s_waitcnt lgkmcnt(4)
	v_pk_mul_f32 v[132:133], v[16:17], v[94:95] op_sel_hi:[1,0]
	v_pk_mul_f32 v[24:25], v[16:17], v[20:21] op_sel_hi:[1,0]
	v_pk_fma_f32 v[132:133], v[12:13], v[94:95], v[132:133] op_sel:[0,1,0]
	v_pk_fma_f32 v[24:25], v[12:13], v[20:21], v[24:25] op_sel:[0,1,0]
	v_pk_fma_f32 v[132:133], v[18:19], v[96:97], v[132:133] op_sel_hi:[1,0,1]
	v_pk_fma_f32 v[24:25], v[18:19], v[22:23], v[24:25] op_sel_hi:[1,0,1]
	v_pk_fma_f32 v[132:133], v[14:15], v[96:97], v[132:133] op_sel:[0,1,0]
	v_pk_fma_f32 v[24:25], v[14:15], v[22:23], v[24:25] op_sel:[0,1,0]
	v_cvt_pk_f16_f32 v24, v24, v25
	v_add_f32_dpp v132, v132, v132 quad_perm:[1,0,3,2] row_mask:0xf bank_mask:0xf bound_ctrl:1
	v_add_f32_dpp v133, v133, v133 quad_perm:[1,0,3,2] row_mask:0xf bank_mask:0xf bound_ctrl:1
	ds_write_b32 v93, v24 offset:2048
	ds_read_b128 v[32:35], v114 offset:13312
	ds_read_b128 v[24:27], v114 offset:17408
	ds_read_b128 v[28:31], v114 offset:9216
	ds_read_b128 v[20:23], v114 offset:1024
	s_waitcnt lgkmcnt(5)
	v_pk_fma_f32 v[16:17], v[120:121], v[130:131], v[16:17] op_sel_hi:[0,1,1]
	v_add_f32_dpp v132, v132, v132 quad_perm:[2,3,0,1] row_mask:0xf bank_mask:0xf bound_ctrl:1
	v_add_f32_dpp v133, v133, v133 quad_perm:[2,3,0,1] row_mask:0xf bank_mask:0xf bound_ctrl:1
	v_pk_fma_f32 v[12:13], v[120:121], v[130:131], v[12:13] op_sel:[1,0,0]
	v_add_f32_dpp v132, v132, v132 row_half_mirror row_mask:0xf bank_mask:0xf bound_ctrl:1
	v_add_f32_dpp v133, v133, v133 row_half_mirror row_mask:0xf bank_mask:0xf bound_ctrl:1
	v_pk_fma_f32 v[18:19], v[122:123], v[130:131], v[18:19] op_sel_hi:[0,1,1]
	v_pk_fma_f32 v[14:15], v[122:123], v[130:131], v[14:15] op_sel:[1,0,0]
	v_add_f32_dpp v132, v132, v132 row_mirror row_mask:0xf bank_mask:0xf bound_ctrl:1
	v_add_f32_dpp v133, v133, v133 row_mirror row_mask:0xf bank_mask:0xf bound_ctrl:1
	v_pk_fma_f32 v[16:17], v[116:117], v[132:133], v[16:17] op_sel_hi:[0,1,1]
	v_pk_fma_f32 v[12:13], v[116:117], v[132:133], v[12:13] op_sel:[1,0,0]
	v_pk_fma_f32 v[18:19], v[118:119], v[132:133], v[18:19] op_sel_hi:[0,1,1]
	v_pk_fma_f32 v[14:15], v[118:119], v[132:133], v[14:15] op_sel:[1,0,0]
	ds_read_b64 v[90:91], v115 offset:20992
	v_pk_mul_f32 v[94:95], v[16:17], v[124:125] op_sel_hi:[1,0]
	v_pk_fma_f32 v[94:95], v[12:13], v[124:125], v[94:95] op_sel:[0,1,0]
	v_pk_fma_f32 v[94:95], v[18:19], v[126:127], v[94:95] op_sel_hi:[1,0,1]
	v_pk_fma_f32 v[94:95], v[14:15], v[126:127], v[94:95] op_sel:[0,1,0]
	v_cvt_pk_f16_f32 v94, v94, v95
	ds_write_b32 v93, v94 offset:3072
	s_waitcnt lgkmcnt(0)
	v_pk_mul_f32 v[132:133], v[16:17], v[32:33] op_sel_hi:[1,0]
	v_pk_fma_f32 v[132:133], v[12:13], v[32:33], v[132:133] op_sel:[0,1,0]
	v_pk_fma_f32 v[132:133], v[18:19], v[34:35], v[132:133] op_sel_hi:[1,0,1]
	v_pk_fma_f32 v[132:133], v[14:15], v[34:35], v[132:133] op_sel:[0,1,0]
	v_pk_fma_f32 v[16:17], v[28:29], v[90:91], v[16:17] op_sel_hi:[0,1,1]
	v_pk_fma_f32 v[12:13], v[28:29], v[90:91], v[12:13] op_sel:[1,0,0]
	v_add_f32_dpp v132, v132, v132 quad_perm:[1,0,3,2] row_mask:0xf bank_mask:0xf bound_ctrl:1
	v_add_f32_dpp v133, v133, v133 quad_perm:[1,0,3,2] row_mask:0xf bank_mask:0xf bound_ctrl:1
	v_pk_fma_f32 v[18:19], v[30:31], v[90:91], v[18:19] op_sel_hi:[0,1,1]
	v_add_f32_dpp v132, v132, v132 quad_perm:[2,3,0,1] row_mask:0xf bank_mask:0xf bound_ctrl:1
	v_add_f32_dpp v133, v133, v133 quad_perm:[2,3,0,1] row_mask:0xf bank_mask:0xf bound_ctrl:1
	v_pk_fma_f32 v[14:15], v[30:31], v[90:91], v[14:15] op_sel:[1,0,0]
	v_add_f32_dpp v132, v132, v132 row_half_mirror row_mask:0xf bank_mask:0xf bound_ctrl:1
	v_add_f32_dpp v133, v133, v133 row_half_mirror row_mask:0xf bank_mask:0xf bound_ctrl:1
	ds_read_b128 v[94:97], v42 offset:13312
	ds_read_b128 v[116:119], v42 offset:17408
	ds_read_b128 v[120:123], v42 offset:9216
	ds_read_b128 v[124:127], v42 offset:1024
	ds_read_b64 v[130:131], v92 offset:512
	v_add_f32_dpp v132, v132, v132 row_mirror row_mask:0xf bank_mask:0xf bound_ctrl:1
	v_add_f32_dpp v133, v133, v133 row_mirror row_mask:0xf bank_mask:0xf bound_ctrl:1
	v_pk_fma_f32 v[16:17], v[24:25], v[132:133], v[16:17] op_sel_hi:[0,1,1]
	v_pk_fma_f32 v[12:13], v[24:25], v[132:133], v[12:13] op_sel:[1,0,0]
	v_pk_fma_f32 v[18:19], v[26:27], v[132:133], v[18:19] op_sel_hi:[0,1,1]
	v_pk_fma_f32 v[14:15], v[26:27], v[132:133], v[14:15] op_sel:[1,0,0]
	s_waitcnt lgkmcnt(4)
	v_pk_mul_f32 v[132:133], v[16:17], v[94:95] op_sel_hi:[1,0]
	v_pk_mul_f32 v[24:25], v[16:17], v[20:21] op_sel_hi:[1,0]
	v_pk_fma_f32 v[132:133], v[12:13], v[94:95], v[132:133] op_sel:[0,1,0]
	v_pk_fma_f32 v[24:25], v[12:13], v[20:21], v[24:25] op_sel:[0,1,0]
	v_pk_fma_f32 v[132:133], v[18:19], v[96:97], v[132:133] op_sel_hi:[1,0,1]
	v_pk_fma_f32 v[24:25], v[18:19], v[22:23], v[24:25] op_sel_hi:[1,0,1]
	v_pk_fma_f32 v[132:133], v[14:15], v[96:97], v[132:133] op_sel:[0,1,0]
	v_pk_fma_f32 v[24:25], v[14:15], v[22:23], v[24:25] op_sel:[0,1,0]
	v_cvt_pk_f16_f32 v24, v24, v25
	v_add_f32_dpp v132, v132, v132 quad_perm:[1,0,3,2] row_mask:0xf bank_mask:0xf bound_ctrl:1
	v_add_f32_dpp v133, v133, v133 quad_perm:[1,0,3,2] row_mask:0xf bank_mask:0xf bound_ctrl:1
	ds_write_b32 v93, v24 offset:4096
	ds_read_b128 v[32:35], v114 offset:13824
	ds_read_b128 v[24:27], v114 offset:17920
	ds_read_b128 v[28:31], v114 offset:9728
	ds_read_b128 v[20:23], v114 offset:1536
	s_waitcnt lgkmcnt(5)
	v_pk_fma_f32 v[16:17], v[120:121], v[130:131], v[16:17] op_sel_hi:[0,1,1]
	v_add_f32_dpp v132, v132, v132 quad_perm:[2,3,0,1] row_mask:0xf bank_mask:0xf bound_ctrl:1
	v_add_f32_dpp v133, v133, v133 quad_perm:[2,3,0,1] row_mask:0xf bank_mask:0xf bound_ctrl:1
	v_pk_fma_f32 v[12:13], v[120:121], v[130:131], v[12:13] op_sel:[1,0,0]
	v_add_f32_dpp v132, v132, v132 row_half_mirror row_mask:0xf bank_mask:0xf bound_ctrl:1
	v_add_f32_dpp v133, v133, v133 row_half_mirror row_mask:0xf bank_mask:0xf bound_ctrl:1
	v_pk_fma_f32 v[18:19], v[122:123], v[130:131], v[18:19] op_sel_hi:[0,1,1]
	v_pk_fma_f32 v[14:15], v[122:123], v[130:131], v[14:15] op_sel:[1,0,0]
	v_add_f32_dpp v132, v132, v132 row_mirror row_mask:0xf bank_mask:0xf bound_ctrl:1
	v_add_f32_dpp v133, v133, v133 row_mirror row_mask:0xf bank_mask:0xf bound_ctrl:1
	v_pk_fma_f32 v[16:17], v[116:117], v[132:133], v[16:17] op_sel_hi:[0,1,1]
	v_pk_fma_f32 v[12:13], v[116:117], v[132:133], v[12:13] op_sel:[1,0,0]
	v_pk_fma_f32 v[18:19], v[118:119], v[132:133], v[18:19] op_sel_hi:[0,1,1]
	v_pk_fma_f32 v[14:15], v[118:119], v[132:133], v[14:15] op_sel:[1,0,0]
	ds_read_b64 v[90:91], v115 offset:21248
	v_pk_mul_f32 v[94:95], v[16:17], v[124:125] op_sel_hi:[1,0]
	v_pk_fma_f32 v[94:95], v[12:13], v[124:125], v[94:95] op_sel:[0,1,0]
	v_pk_fma_f32 v[94:95], v[18:19], v[126:127], v[94:95] op_sel_hi:[1,0,1]
	v_pk_fma_f32 v[94:95], v[14:15], v[126:127], v[94:95] op_sel:[0,1,0]
	v_cvt_pk_f16_f32 v94, v94, v95
	ds_write_b32 v93, v94 offset:5120
	s_waitcnt lgkmcnt(0)
	v_pk_mul_f32 v[132:133], v[16:17], v[32:33] op_sel_hi:[1,0]
	v_pk_fma_f32 v[132:133], v[12:13], v[32:33], v[132:133] op_sel:[0,1,0]
	v_pk_fma_f32 v[132:133], v[18:19], v[34:35], v[132:133] op_sel_hi:[1,0,1]
	v_pk_fma_f32 v[132:133], v[14:15], v[34:35], v[132:133] op_sel:[0,1,0]
	v_pk_fma_f32 v[16:17], v[28:29], v[90:91], v[16:17] op_sel_hi:[0,1,1]
	v_pk_fma_f32 v[12:13], v[28:29], v[90:91], v[12:13] op_sel:[1,0,0]
	v_add_f32_dpp v132, v132, v132 quad_perm:[1,0,3,2] row_mask:0xf bank_mask:0xf bound_ctrl:1
	v_add_f32_dpp v133, v133, v133 quad_perm:[1,0,3,2] row_mask:0xf bank_mask:0xf bound_ctrl:1
	v_pk_fma_f32 v[18:19], v[30:31], v[90:91], v[18:19] op_sel_hi:[0,1,1]
	v_add_f32_dpp v132, v132, v132 quad_perm:[2,3,0,1] row_mask:0xf bank_mask:0xf bound_ctrl:1
	v_add_f32_dpp v133, v133, v133 quad_perm:[2,3,0,1] row_mask:0xf bank_mask:0xf bound_ctrl:1
	v_pk_fma_f32 v[14:15], v[30:31], v[90:91], v[14:15] op_sel:[1,0,0]
	v_add_f32_dpp v132, v132, v132 row_half_mirror row_mask:0xf bank_mask:0xf bound_ctrl:1
	v_add_f32_dpp v133, v133, v133 row_half_mirror row_mask:0xf bank_mask:0xf bound_ctrl:1
	ds_read_b128 v[94:97], v42 offset:13824
	ds_read_b128 v[116:119], v42 offset:17920
	ds_read_b128 v[120:123], v42 offset:9728
	ds_read_b128 v[124:127], v42 offset:1536
	ds_read_b64 v[130:131], v92 offset:768
	v_add_f32_dpp v132, v132, v132 row_mirror row_mask:0xf bank_mask:0xf bound_ctrl:1
	v_add_f32_dpp v133, v133, v133 row_mirror row_mask:0xf bank_mask:0xf bound_ctrl:1
	v_pk_fma_f32 v[16:17], v[24:25], v[132:133], v[16:17] op_sel_hi:[0,1,1]
	v_pk_fma_f32 v[12:13], v[24:25], v[132:133], v[12:13] op_sel:[1,0,0]
	v_pk_fma_f32 v[18:19], v[26:27], v[132:133], v[18:19] op_sel_hi:[0,1,1]
	v_pk_fma_f32 v[14:15], v[26:27], v[132:133], v[14:15] op_sel:[1,0,0]
	s_waitcnt lgkmcnt(4)
	v_pk_mul_f32 v[132:133], v[16:17], v[94:95] op_sel_hi:[1,0]
	v_pk_mul_f32 v[24:25], v[16:17], v[20:21] op_sel_hi:[1,0]
	v_pk_fma_f32 v[132:133], v[12:13], v[94:95], v[132:133] op_sel:[0,1,0]
	v_pk_fma_f32 v[24:25], v[12:13], v[20:21], v[24:25] op_sel:[0,1,0]
	v_pk_fma_f32 v[132:133], v[18:19], v[96:97], v[132:133] op_sel_hi:[1,0,1]
	v_pk_fma_f32 v[24:25], v[18:19], v[22:23], v[24:25] op_sel_hi:[1,0,1]
	v_pk_fma_f32 v[132:133], v[14:15], v[96:97], v[132:133] op_sel:[0,1,0]
	v_pk_fma_f32 v[24:25], v[14:15], v[22:23], v[24:25] op_sel:[0,1,0]
	v_cvt_pk_f16_f32 v24, v24, v25
	v_add_f32_dpp v132, v132, v132 quad_perm:[1,0,3,2] row_mask:0xf bank_mask:0xf bound_ctrl:1
	v_add_f32_dpp v133, v133, v133 quad_perm:[1,0,3,2] row_mask:0xf bank_mask:0xf bound_ctrl:1
	ds_write_b32 v93, v24 offset:6144
	ds_read_b128 v[32:35], v114 offset:14336
	ds_read_b128 v[24:27], v114 offset:18432
	ds_read_b128 v[28:31], v114 offset:10240
	ds_read_b128 v[20:23], v114 offset:2048
	s_waitcnt lgkmcnt(5)
	v_pk_fma_f32 v[16:17], v[120:121], v[130:131], v[16:17] op_sel_hi:[0,1,1]
	v_add_f32_dpp v132, v132, v132 quad_perm:[2,3,0,1] row_mask:0xf bank_mask:0xf bound_ctrl:1
	v_add_f32_dpp v133, v133, v133 quad_perm:[2,3,0,1] row_mask:0xf bank_mask:0xf bound_ctrl:1
	v_pk_fma_f32 v[12:13], v[120:121], v[130:131], v[12:13] op_sel:[1,0,0]
	v_add_f32_dpp v132, v132, v132 row_half_mirror row_mask:0xf bank_mask:0xf bound_ctrl:1
	v_add_f32_dpp v133, v133, v133 row_half_mirror row_mask:0xf bank_mask:0xf bound_ctrl:1
	v_pk_fma_f32 v[18:19], v[122:123], v[130:131], v[18:19] op_sel_hi:[0,1,1]
	v_pk_fma_f32 v[14:15], v[122:123], v[130:131], v[14:15] op_sel:[1,0,0]
	v_add_f32_dpp v132, v132, v132 row_mirror row_mask:0xf bank_mask:0xf bound_ctrl:1
	v_add_f32_dpp v133, v133, v133 row_mirror row_mask:0xf bank_mask:0xf bound_ctrl:1
	v_pk_fma_f32 v[16:17], v[116:117], v[132:133], v[16:17] op_sel_hi:[0,1,1]
	v_pk_fma_f32 v[12:13], v[116:117], v[132:133], v[12:13] op_sel:[1,0,0]
	v_pk_fma_f32 v[18:19], v[118:119], v[132:133], v[18:19] op_sel_hi:[0,1,1]
	v_pk_fma_f32 v[14:15], v[118:119], v[132:133], v[14:15] op_sel:[1,0,0]
	ds_read_b64 v[90:91], v115 offset:21504
	v_pk_mul_f32 v[94:95], v[16:17], v[124:125] op_sel_hi:[1,0]
	v_pk_fma_f32 v[94:95], v[12:13], v[124:125], v[94:95] op_sel:[0,1,0]
	v_pk_fma_f32 v[94:95], v[18:19], v[126:127], v[94:95] op_sel_hi:[1,0,1]
	v_pk_fma_f32 v[94:95], v[14:15], v[126:127], v[94:95] op_sel:[0,1,0]
	v_cvt_pk_f16_f32 v94, v94, v95
	ds_write_b32 v93, v94 offset:7168
	s_waitcnt lgkmcnt(0)
	v_pk_mul_f32 v[132:133], v[16:17], v[32:33] op_sel_hi:[1,0]
	v_pk_fma_f32 v[132:133], v[12:13], v[32:33], v[132:133] op_sel:[0,1,0]
	v_pk_fma_f32 v[132:133], v[18:19], v[34:35], v[132:133] op_sel_hi:[1,0,1]
	v_pk_fma_f32 v[132:133], v[14:15], v[34:35], v[132:133] op_sel:[0,1,0]
	v_pk_fma_f32 v[16:17], v[28:29], v[90:91], v[16:17] op_sel_hi:[0,1,1]
	v_pk_fma_f32 v[12:13], v[28:29], v[90:91], v[12:13] op_sel:[1,0,0]
	v_add_f32_dpp v132, v132, v132 quad_perm:[1,0,3,2] row_mask:0xf bank_mask:0xf bound_ctrl:1
	v_add_f32_dpp v133, v133, v133 quad_perm:[1,0,3,2] row_mask:0xf bank_mask:0xf bound_ctrl:1
	v_pk_fma_f32 v[18:19], v[30:31], v[90:91], v[18:19] op_sel_hi:[0,1,1]
	v_add_f32_dpp v132, v132, v132 quad_perm:[2,3,0,1] row_mask:0xf bank_mask:0xf bound_ctrl:1
	v_add_f32_dpp v133, v133, v133 quad_perm:[2,3,0,1] row_mask:0xf bank_mask:0xf bound_ctrl:1
	v_pk_fma_f32 v[14:15], v[30:31], v[90:91], v[14:15] op_sel:[1,0,0]
	v_add_f32_dpp v132, v132, v132 row_half_mirror row_mask:0xf bank_mask:0xf bound_ctrl:1
	v_add_f32_dpp v133, v133, v133 row_half_mirror row_mask:0xf bank_mask:0xf bound_ctrl:1
	ds_read_b128 v[94:97], v42 offset:14336
	ds_read_b128 v[116:119], v42 offset:18432
	ds_read_b128 v[120:123], v42 offset:10240
	ds_read_b128 v[124:127], v42 offset:2048
	ds_read_b64 v[130:131], v92 offset:1024
	v_add_f32_dpp v132, v132, v132 row_mirror row_mask:0xf bank_mask:0xf bound_ctrl:1
	v_add_f32_dpp v133, v133, v133 row_mirror row_mask:0xf bank_mask:0xf bound_ctrl:1
	v_pk_fma_f32 v[16:17], v[24:25], v[132:133], v[16:17] op_sel_hi:[0,1,1]
	v_pk_fma_f32 v[12:13], v[24:25], v[132:133], v[12:13] op_sel:[1,0,0]
	v_pk_fma_f32 v[18:19], v[26:27], v[132:133], v[18:19] op_sel_hi:[0,1,1]
	v_pk_fma_f32 v[14:15], v[26:27], v[132:133], v[14:15] op_sel:[1,0,0]
	s_waitcnt lgkmcnt(4)
	v_pk_mul_f32 v[132:133], v[16:17], v[94:95] op_sel_hi:[1,0]
	v_pk_mul_f32 v[24:25], v[16:17], v[20:21] op_sel_hi:[1,0]
	v_pk_fma_f32 v[132:133], v[12:13], v[94:95], v[132:133] op_sel:[0,1,0]
	v_pk_fma_f32 v[24:25], v[12:13], v[20:21], v[24:25] op_sel:[0,1,0]
	v_pk_fma_f32 v[132:133], v[18:19], v[96:97], v[132:133] op_sel_hi:[1,0,1]
	v_pk_fma_f32 v[24:25], v[18:19], v[22:23], v[24:25] op_sel_hi:[1,0,1]
	v_pk_fma_f32 v[132:133], v[14:15], v[96:97], v[132:133] op_sel:[0,1,0]
	v_pk_fma_f32 v[24:25], v[14:15], v[22:23], v[24:25] op_sel:[0,1,0]
	v_cvt_pk_f16_f32 v24, v24, v25
	v_add_f32_dpp v132, v132, v132 quad_perm:[1,0,3,2] row_mask:0xf bank_mask:0xf bound_ctrl:1
	v_add_f32_dpp v133, v133, v133 quad_perm:[1,0,3,2] row_mask:0xf bank_mask:0xf bound_ctrl:1
	ds_write_b32 v93, v24 offset:8192
	ds_read_b128 v[32:35], v114 offset:14848
	ds_read_b128 v[24:27], v114 offset:18944
	ds_read_b128 v[28:31], v114 offset:10752
	ds_read_b128 v[20:23], v114 offset:2560
	s_waitcnt lgkmcnt(5)
	v_pk_fma_f32 v[16:17], v[120:121], v[130:131], v[16:17] op_sel_hi:[0,1,1]
	v_add_f32_dpp v132, v132, v132 quad_perm:[2,3,0,1] row_mask:0xf bank_mask:0xf bound_ctrl:1
	v_add_f32_dpp v133, v133, v133 quad_perm:[2,3,0,1] row_mask:0xf bank_mask:0xf bound_ctrl:1
	v_pk_fma_f32 v[12:13], v[120:121], v[130:131], v[12:13] op_sel:[1,0,0]
	v_add_f32_dpp v132, v132, v132 row_half_mirror row_mask:0xf bank_mask:0xf bound_ctrl:1
	v_add_f32_dpp v133, v133, v133 row_half_mirror row_mask:0xf bank_mask:0xf bound_ctrl:1
	v_pk_fma_f32 v[18:19], v[122:123], v[130:131], v[18:19] op_sel_hi:[0,1,1]
	v_pk_fma_f32 v[14:15], v[122:123], v[130:131], v[14:15] op_sel:[1,0,0]
	v_add_f32_dpp v132, v132, v132 row_mirror row_mask:0xf bank_mask:0xf bound_ctrl:1
	v_add_f32_dpp v133, v133, v133 row_mirror row_mask:0xf bank_mask:0xf bound_ctrl:1
	v_pk_fma_f32 v[16:17], v[116:117], v[132:133], v[16:17] op_sel_hi:[0,1,1]
	v_pk_fma_f32 v[12:13], v[116:117], v[132:133], v[12:13] op_sel:[1,0,0]
	v_pk_fma_f32 v[18:19], v[118:119], v[132:133], v[18:19] op_sel_hi:[0,1,1]
	v_pk_fma_f32 v[14:15], v[118:119], v[132:133], v[14:15] op_sel:[1,0,0]
	ds_read_b64 v[90:91], v115 offset:21760
	v_pk_mul_f32 v[94:95], v[16:17], v[124:125] op_sel_hi:[1,0]
	v_pk_fma_f32 v[94:95], v[12:13], v[124:125], v[94:95] op_sel:[0,1,0]
	v_pk_fma_f32 v[94:95], v[18:19], v[126:127], v[94:95] op_sel_hi:[1,0,1]
	v_pk_fma_f32 v[94:95], v[14:15], v[126:127], v[94:95] op_sel:[0,1,0]
	v_cvt_pk_f16_f32 v94, v94, v95
	ds_write_b32 v93, v94 offset:9216
	s_waitcnt lgkmcnt(0)
	v_pk_mul_f32 v[132:133], v[16:17], v[32:33] op_sel_hi:[1,0]
	v_pk_fma_f32 v[132:133], v[12:13], v[32:33], v[132:133] op_sel:[0,1,0]
	v_pk_fma_f32 v[132:133], v[18:19], v[34:35], v[132:133] op_sel_hi:[1,0,1]
	v_pk_fma_f32 v[132:133], v[14:15], v[34:35], v[132:133] op_sel:[0,1,0]
	v_pk_fma_f32 v[16:17], v[28:29], v[90:91], v[16:17] op_sel_hi:[0,1,1]
	v_pk_fma_f32 v[12:13], v[28:29], v[90:91], v[12:13] op_sel:[1,0,0]
	v_add_f32_dpp v132, v132, v132 quad_perm:[1,0,3,2] row_mask:0xf bank_mask:0xf bound_ctrl:1
	v_add_f32_dpp v133, v133, v133 quad_perm:[1,0,3,2] row_mask:0xf bank_mask:0xf bound_ctrl:1
	v_pk_fma_f32 v[18:19], v[30:31], v[90:91], v[18:19] op_sel_hi:[0,1,1]
	v_add_f32_dpp v132, v132, v132 quad_perm:[2,3,0,1] row_mask:0xf bank_mask:0xf bound_ctrl:1
	v_add_f32_dpp v133, v133, v133 quad_perm:[2,3,0,1] row_mask:0xf bank_mask:0xf bound_ctrl:1
	v_pk_fma_f32 v[14:15], v[30:31], v[90:91], v[14:15] op_sel:[1,0,0]
	v_add_f32_dpp v132, v132, v132 row_half_mirror row_mask:0xf bank_mask:0xf bound_ctrl:1
	v_add_f32_dpp v133, v133, v133 row_half_mirror row_mask:0xf bank_mask:0xf bound_ctrl:1
	ds_read_b128 v[94:97], v42 offset:14848
	ds_read_b128 v[116:119], v42 offset:18944
	ds_read_b128 v[120:123], v42 offset:10752
	ds_read_b128 v[124:127], v42 offset:2560
	ds_read_b64 v[130:131], v92 offset:1280
	v_add_f32_dpp v132, v132, v132 row_mirror row_mask:0xf bank_mask:0xf bound_ctrl:1
	v_add_f32_dpp v133, v133, v133 row_mirror row_mask:0xf bank_mask:0xf bound_ctrl:1
	v_pk_fma_f32 v[16:17], v[24:25], v[132:133], v[16:17] op_sel_hi:[0,1,1]
	v_pk_fma_f32 v[12:13], v[24:25], v[132:133], v[12:13] op_sel:[1,0,0]
	v_pk_fma_f32 v[18:19], v[26:27], v[132:133], v[18:19] op_sel_hi:[0,1,1]
	v_pk_fma_f32 v[14:15], v[26:27], v[132:133], v[14:15] op_sel:[1,0,0]
	s_waitcnt lgkmcnt(4)
	v_pk_mul_f32 v[132:133], v[16:17], v[94:95] op_sel_hi:[1,0]
	v_pk_mul_f32 v[24:25], v[16:17], v[20:21] op_sel_hi:[1,0]
	v_pk_fma_f32 v[132:133], v[12:13], v[94:95], v[132:133] op_sel:[0,1,0]
	v_pk_fma_f32 v[24:25], v[12:13], v[20:21], v[24:25] op_sel:[0,1,0]
	v_pk_fma_f32 v[132:133], v[18:19], v[96:97], v[132:133] op_sel_hi:[1,0,1]
	v_pk_fma_f32 v[24:25], v[18:19], v[22:23], v[24:25] op_sel_hi:[1,0,1]
	v_pk_fma_f32 v[132:133], v[14:15], v[96:97], v[132:133] op_sel:[0,1,0]
	v_pk_fma_f32 v[24:25], v[14:15], v[22:23], v[24:25] op_sel:[0,1,0]
	v_cvt_pk_f16_f32 v24, v24, v25
	v_add_f32_dpp v132, v132, v132 quad_perm:[1,0,3,2] row_mask:0xf bank_mask:0xf bound_ctrl:1
	v_add_f32_dpp v133, v133, v133 quad_perm:[1,0,3,2] row_mask:0xf bank_mask:0xf bound_ctrl:1
	ds_write_b32 v93, v24 offset:10240
	ds_read_b128 v[32:35], v114 offset:15360
	ds_read_b128 v[24:27], v114 offset:19456
	ds_read_b128 v[28:31], v114 offset:11264
	ds_read_b128 v[20:23], v114 offset:3072
	s_waitcnt lgkmcnt(5)
	v_pk_fma_f32 v[16:17], v[120:121], v[130:131], v[16:17] op_sel_hi:[0,1,1]
	v_add_f32_dpp v132, v132, v132 quad_perm:[2,3,0,1] row_mask:0xf bank_mask:0xf bound_ctrl:1
	v_add_f32_dpp v133, v133, v133 quad_perm:[2,3,0,1] row_mask:0xf bank_mask:0xf bound_ctrl:1
	v_pk_fma_f32 v[12:13], v[120:121], v[130:131], v[12:13] op_sel:[1,0,0]
	v_add_f32_dpp v132, v132, v132 row_half_mirror row_mask:0xf bank_mask:0xf bound_ctrl:1
	v_add_f32_dpp v133, v133, v133 row_half_mirror row_mask:0xf bank_mask:0xf bound_ctrl:1
	v_pk_fma_f32 v[18:19], v[122:123], v[130:131], v[18:19] op_sel_hi:[0,1,1]
	v_pk_fma_f32 v[14:15], v[122:123], v[130:131], v[14:15] op_sel:[1,0,0]
	v_add_f32_dpp v132, v132, v132 row_mirror row_mask:0xf bank_mask:0xf bound_ctrl:1
	v_add_f32_dpp v133, v133, v133 row_mirror row_mask:0xf bank_mask:0xf bound_ctrl:1
	v_pk_fma_f32 v[16:17], v[116:117], v[132:133], v[16:17] op_sel_hi:[0,1,1]
	v_pk_fma_f32 v[12:13], v[116:117], v[132:133], v[12:13] op_sel:[1,0,0]
	v_pk_fma_f32 v[18:19], v[118:119], v[132:133], v[18:19] op_sel_hi:[0,1,1]
	v_pk_fma_f32 v[14:15], v[118:119], v[132:133], v[14:15] op_sel:[1,0,0]
	ds_read_b64 v[90:91], v115 offset:22016
	v_pk_mul_f32 v[94:95], v[16:17], v[124:125] op_sel_hi:[1,0]
	v_pk_fma_f32 v[94:95], v[12:13], v[124:125], v[94:95] op_sel:[0,1,0]
	v_pk_fma_f32 v[94:95], v[18:19], v[126:127], v[94:95] op_sel_hi:[1,0,1]
	v_pk_fma_f32 v[94:95], v[14:15], v[126:127], v[94:95] op_sel:[0,1,0]
	v_cvt_pk_f16_f32 v94, v94, v95
	ds_write_b32 v93, v94 offset:11264
	s_waitcnt lgkmcnt(0)
	v_pk_mul_f32 v[132:133], v[16:17], v[32:33] op_sel_hi:[1,0]
	v_pk_fma_f32 v[132:133], v[12:13], v[32:33], v[132:133] op_sel:[0,1,0]
	v_pk_fma_f32 v[132:133], v[18:19], v[34:35], v[132:133] op_sel_hi:[1,0,1]
	v_pk_fma_f32 v[132:133], v[14:15], v[34:35], v[132:133] op_sel:[0,1,0]
	v_pk_fma_f32 v[16:17], v[28:29], v[90:91], v[16:17] op_sel_hi:[0,1,1]
	v_pk_fma_f32 v[12:13], v[28:29], v[90:91], v[12:13] op_sel:[1,0,0]
	v_add_f32_dpp v132, v132, v132 quad_perm:[1,0,3,2] row_mask:0xf bank_mask:0xf bound_ctrl:1
	v_add_f32_dpp v133, v133, v133 quad_perm:[1,0,3,2] row_mask:0xf bank_mask:0xf bound_ctrl:1
	v_pk_fma_f32 v[18:19], v[30:31], v[90:91], v[18:19] op_sel_hi:[0,1,1]
	v_add_f32_dpp v132, v132, v132 quad_perm:[2,3,0,1] row_mask:0xf bank_mask:0xf bound_ctrl:1
	v_add_f32_dpp v133, v133, v133 quad_perm:[2,3,0,1] row_mask:0xf bank_mask:0xf bound_ctrl:1
	v_pk_fma_f32 v[14:15], v[30:31], v[90:91], v[14:15] op_sel:[1,0,0]
	v_add_f32_dpp v132, v132, v132 row_half_mirror row_mask:0xf bank_mask:0xf bound_ctrl:1
	v_add_f32_dpp v133, v133, v133 row_half_mirror row_mask:0xf bank_mask:0xf bound_ctrl:1
	ds_read_b128 v[94:97], v42 offset:15360
	ds_read_b128 v[116:119], v42 offset:19456
	ds_read_b128 v[120:123], v42 offset:11264
	ds_read_b128 v[124:127], v42 offset:3072
	ds_read_b64 v[130:131], v92 offset:1536
	v_add_f32_dpp v132, v132, v132 row_mirror row_mask:0xf bank_mask:0xf bound_ctrl:1
	v_add_f32_dpp v133, v133, v133 row_mirror row_mask:0xf bank_mask:0xf bound_ctrl:1
	v_pk_fma_f32 v[16:17], v[24:25], v[132:133], v[16:17] op_sel_hi:[0,1,1]
	v_pk_fma_f32 v[12:13], v[24:25], v[132:133], v[12:13] op_sel:[1,0,0]
	v_pk_fma_f32 v[18:19], v[26:27], v[132:133], v[18:19] op_sel_hi:[0,1,1]
	v_pk_fma_f32 v[14:15], v[26:27], v[132:133], v[14:15] op_sel:[1,0,0]
	s_waitcnt lgkmcnt(4)
	v_pk_mul_f32 v[132:133], v[16:17], v[94:95] op_sel_hi:[1,0]
	v_pk_mul_f32 v[24:25], v[16:17], v[20:21] op_sel_hi:[1,0]
	v_pk_fma_f32 v[132:133], v[12:13], v[94:95], v[132:133] op_sel:[0,1,0]
	v_pk_fma_f32 v[24:25], v[12:13], v[20:21], v[24:25] op_sel:[0,1,0]
	v_pk_fma_f32 v[132:133], v[18:19], v[96:97], v[132:133] op_sel_hi:[1,0,1]
	v_pk_fma_f32 v[24:25], v[18:19], v[22:23], v[24:25] op_sel_hi:[1,0,1]
	v_pk_fma_f32 v[132:133], v[14:15], v[96:97], v[132:133] op_sel:[0,1,0]
	v_pk_fma_f32 v[24:25], v[14:15], v[22:23], v[24:25] op_sel:[0,1,0]
	v_cvt_pk_f16_f32 v24, v24, v25
	v_add_f32_dpp v132, v132, v132 quad_perm:[1,0,3,2] row_mask:0xf bank_mask:0xf bound_ctrl:1
	v_add_f32_dpp v133, v133, v133 quad_perm:[1,0,3,2] row_mask:0xf bank_mask:0xf bound_ctrl:1
	ds_write_b32 v93, v24 offset:12288
	ds_read_b128 v[32:35], v114 offset:15872
	ds_read_b128 v[24:27], v114 offset:19968
	ds_read_b128 v[28:31], v114 offset:11776
	ds_read_b128 v[20:23], v114 offset:3584
	s_waitcnt lgkmcnt(5)
	v_pk_fma_f32 v[16:17], v[120:121], v[130:131], v[16:17] op_sel_hi:[0,1,1]
	v_add_f32_dpp v132, v132, v132 quad_perm:[2,3,0,1] row_mask:0xf bank_mask:0xf bound_ctrl:1
	v_add_f32_dpp v133, v133, v133 quad_perm:[2,3,0,1] row_mask:0xf bank_mask:0xf bound_ctrl:1
	v_pk_fma_f32 v[12:13], v[120:121], v[130:131], v[12:13] op_sel:[1,0,0]
	v_add_f32_dpp v132, v132, v132 row_half_mirror row_mask:0xf bank_mask:0xf bound_ctrl:1
	v_add_f32_dpp v133, v133, v133 row_half_mirror row_mask:0xf bank_mask:0xf bound_ctrl:1
	v_pk_fma_f32 v[18:19], v[122:123], v[130:131], v[18:19] op_sel_hi:[0,1,1]
	v_pk_fma_f32 v[14:15], v[122:123], v[130:131], v[14:15] op_sel:[1,0,0]
	v_add_f32_dpp v132, v132, v132 row_mirror row_mask:0xf bank_mask:0xf bound_ctrl:1
	v_add_f32_dpp v133, v133, v133 row_mirror row_mask:0xf bank_mask:0xf bound_ctrl:1
	v_pk_fma_f32 v[16:17], v[116:117], v[132:133], v[16:17] op_sel_hi:[0,1,1]
	v_pk_fma_f32 v[12:13], v[116:117], v[132:133], v[12:13] op_sel:[1,0,0]
	v_pk_fma_f32 v[18:19], v[118:119], v[132:133], v[18:19] op_sel_hi:[0,1,1]
	v_pk_fma_f32 v[14:15], v[118:119], v[132:133], v[14:15] op_sel:[1,0,0]
	ds_read_b64 v[90:91], v115 offset:22272
	v_pk_mul_f32 v[94:95], v[16:17], v[124:125] op_sel_hi:[1,0]
	v_pk_fma_f32 v[94:95], v[12:13], v[124:125], v[94:95] op_sel:[0,1,0]
	v_pk_fma_f32 v[94:95], v[18:19], v[126:127], v[94:95] op_sel_hi:[1,0,1]
	v_pk_fma_f32 v[94:95], v[14:15], v[126:127], v[94:95] op_sel:[0,1,0]
	v_cvt_pk_f16_f32 v94, v94, v95
	ds_write_b32 v93, v94 offset:13312
	s_waitcnt lgkmcnt(0)
	v_pk_mul_f32 v[132:133], v[16:17], v[32:33] op_sel_hi:[1,0]
	v_pk_fma_f32 v[132:133], v[12:13], v[32:33], v[132:133] op_sel:[0,1,0]
	v_pk_fma_f32 v[132:133], v[18:19], v[34:35], v[132:133] op_sel_hi:[1,0,1]
	v_pk_fma_f32 v[132:133], v[14:15], v[34:35], v[132:133] op_sel:[0,1,0]
	v_pk_fma_f32 v[16:17], v[28:29], v[90:91], v[16:17] op_sel_hi:[0,1,1]
	v_pk_fma_f32 v[12:13], v[28:29], v[90:91], v[12:13] op_sel:[1,0,0]
	v_add_f32_dpp v132, v132, v132 quad_perm:[1,0,3,2] row_mask:0xf bank_mask:0xf bound_ctrl:1
	v_add_f32_dpp v133, v133, v133 quad_perm:[1,0,3,2] row_mask:0xf bank_mask:0xf bound_ctrl:1
	v_pk_fma_f32 v[18:19], v[30:31], v[90:91], v[18:19] op_sel_hi:[0,1,1]
	v_add_f32_dpp v132, v132, v132 quad_perm:[2,3,0,1] row_mask:0xf bank_mask:0xf bound_ctrl:1
	v_add_f32_dpp v133, v133, v133 quad_perm:[2,3,0,1] row_mask:0xf bank_mask:0xf bound_ctrl:1
	v_pk_fma_f32 v[14:15], v[30:31], v[90:91], v[14:15] op_sel:[1,0,0]
	v_add_f32_dpp v132, v132, v132 row_half_mirror row_mask:0xf bank_mask:0xf bound_ctrl:1
	v_add_f32_dpp v133, v133, v133 row_half_mirror row_mask:0xf bank_mask:0xf bound_ctrl:1
	ds_read_b128 v[94:97], v42 offset:15872
	ds_read_b128 v[116:119], v42 offset:19968
	ds_read_b128 v[120:123], v42 offset:11776
	ds_read_b128 v[124:127], v42 offset:3584
	ds_read_b64 v[130:131], v92 offset:1792
	v_add_f32_dpp v132, v132, v132 row_mirror row_mask:0xf bank_mask:0xf bound_ctrl:1
	v_add_f32_dpp v133, v133, v133 row_mirror row_mask:0xf bank_mask:0xf bound_ctrl:1
	v_pk_fma_f32 v[16:17], v[24:25], v[132:133], v[16:17] op_sel_hi:[0,1,1]
	v_pk_fma_f32 v[12:13], v[24:25], v[132:133], v[12:13] op_sel:[1,0,0]
	v_pk_fma_f32 v[18:19], v[26:27], v[132:133], v[18:19] op_sel_hi:[0,1,1]
	v_pk_fma_f32 v[14:15], v[26:27], v[132:133], v[14:15] op_sel:[1,0,0]
	s_waitcnt lgkmcnt(4)
	v_pk_mul_f32 v[132:133], v[16:17], v[94:95] op_sel_hi:[1,0]
	v_pk_mul_f32 v[24:25], v[16:17], v[20:21] op_sel_hi:[1,0]
	v_pk_fma_f32 v[132:133], v[12:13], v[94:95], v[132:133] op_sel:[0,1,0]
	v_pk_fma_f32 v[24:25], v[12:13], v[20:21], v[24:25] op_sel:[0,1,0]
	v_pk_fma_f32 v[132:133], v[18:19], v[96:97], v[132:133] op_sel_hi:[1,0,1]
	v_pk_fma_f32 v[24:25], v[18:19], v[22:23], v[24:25] op_sel_hi:[1,0,1]
	v_pk_fma_f32 v[132:133], v[14:15], v[96:97], v[132:133] op_sel:[0,1,0]
	v_pk_fma_f32 v[24:25], v[14:15], v[22:23], v[24:25] op_sel:[0,1,0]
	v_cvt_pk_f16_f32 v24, v24, v25
	v_add_f32_dpp v132, v132, v132 quad_perm:[1,0,3,2] row_mask:0xf bank_mask:0xf bound_ctrl:1
	v_add_f32_dpp v133, v133, v133 quad_perm:[1,0,3,2] row_mask:0xf bank_mask:0xf bound_ctrl:1
	ds_write_b32 v93, v24 offset:14336
	ds_read_b128 v[32:35], v114 offset:15872
	ds_read_b128 v[24:27], v114 offset:19968
	ds_read_b128 v[28:31], v114 offset:11776
	ds_read_b128 v[20:23], v114 offset:3584
	s_waitcnt lgkmcnt(5)
	v_pk_fma_f32 v[16:17], v[120:121], v[130:131], v[16:17] op_sel_hi:[0,1,1]
	v_add_f32_dpp v132, v132, v132 quad_perm:[2,3,0,1] row_mask:0xf bank_mask:0xf bound_ctrl:1
	v_add_f32_dpp v133, v133, v133 quad_perm:[2,3,0,1] row_mask:0xf bank_mask:0xf bound_ctrl:1
	v_pk_fma_f32 v[12:13], v[120:121], v[130:131], v[12:13] op_sel:[1,0,0]
	v_add_f32_dpp v132, v132, v132 row_half_mirror row_mask:0xf bank_mask:0xf bound_ctrl:1
	v_add_f32_dpp v133, v133, v133 row_half_mirror row_mask:0xf bank_mask:0xf bound_ctrl:1
	v_pk_fma_f32 v[18:19], v[122:123], v[130:131], v[18:19] op_sel_hi:[0,1,1]
	v_pk_fma_f32 v[14:15], v[122:123], v[130:131], v[14:15] op_sel:[1,0,0]
	v_add_f32_dpp v132, v132, v132 row_mirror row_mask:0xf bank_mask:0xf bound_ctrl:1
	v_add_f32_dpp v133, v133, v133 row_mirror row_mask:0xf bank_mask:0xf bound_ctrl:1
	v_pk_fma_f32 v[16:17], v[116:117], v[132:133], v[16:17] op_sel_hi:[0,1,1]
	v_pk_fma_f32 v[12:13], v[116:117], v[132:133], v[12:13] op_sel:[1,0,0]
	v_pk_fma_f32 v[18:19], v[118:119], v[132:133], v[18:19] op_sel_hi:[0,1,1]
	v_pk_fma_f32 v[14:15], v[118:119], v[132:133], v[14:15] op_sel:[1,0,0]
	ds_read_b64 v[90:91], v115 offset:22272
	v_pk_mul_f32 v[94:95], v[16:17], v[124:125] op_sel_hi:[1,0]
	v_pk_fma_f32 v[94:95], v[12:13], v[124:125], v[94:95] op_sel:[0,1,0]
	v_pk_fma_f32 v[94:95], v[18:19], v[126:127], v[94:95] op_sel_hi:[1,0,1]
	v_pk_fma_f32 v[94:95], v[14:15], v[126:127], v[94:95] op_sel:[0,1,0]
	v_cvt_pk_f16_f32 v94, v94, v95
	ds_write_b32 v93, v94 offset:15360
	v_swap_b32 v17, v12
	v_swap_b32 v19, v14
	s_waitcnt vmcnt(10) lgkmcnt(1)
	v_cvt_f32_f16_sdwa v91, v60 dst_sel:DWORD dst_unused:UNUSED_PAD src0_sel:WORD_1
	v_cvt_f32_f16_e32 v90, v60
	v_cvt_f32_f16_sdwa v93, v61 dst_sel:DWORD dst_unused:UNUSED_PAD src0_sel:WORD_1
	v_cvt_f32_f16_e32 v92, v61
	s_waitcnt vmcnt(7)
	v_cvt_f32_f16_sdwa v25, v68 dst_sel:DWORD dst_unused:UNUSED_PAD src0_sel:WORD_1
	v_cvt_f32_f16_e32 v24, v68
	v_cvt_f32_f16_sdwa v27, v69 dst_sel:DWORD dst_unused:UNUSED_PAD src0_sel:WORD_1
	v_cvt_f32_f16_e32 v26, v69
	v_pk_mul_f32 v[30:31], v[0:1], v[90:91]
	v_pk_mul_f32 v[28:29], v[2:3], v[92:93]
	v_pk_mul_f32 v[96:97], v[30:31], v[30:31]
	v_pk_mul_f32 v[94:95], v[28:29], v[28:29]
	v_add_f32_e32 v42, v96, v97
	v_cvt_f32_f16_sdwa v33, v58 dst_sel:DWORD dst_unused:UNUSED_PAD src0_sel:WORD_1
	v_cvt_f32_f16_e32 v32, v58
	v_cvt_f32_f16_sdwa v35, v59 dst_sel:DWORD dst_unused:UNUSED_PAD src0_sel:WORD_1
	v_cvt_f32_f16_e32 v34, v59
	v_add_f32_e32 v42, v94, v42
	v_add_f32_e32 v42, v95, v42
	v_pk_add_f32 v[94:95], v[24:25], -1.0 op_sel_hi:[1,0]
	v_pk_add_f32 v[96:97], v[26:27], -1.0 op_sel_hi:[1,0]
	v_pk_fma_f32 v[94:95], v[4:5], v[94:95], 1.0 op_sel_hi:[1,1,0]
	v_pk_fma_f32 v[96:97], v[6:7], v[96:97], 1.0 op_sel_hi:[1,1,0]
	v_pk_mul_f32 v[94:95], v[90:91], v[94:95]
	v_pk_mul_f32 v[96:97], v[92:93], v[96:97]
	v_pk_mul_f32 v[90:91], v[32:33], v[94:95]
	v_pk_mul_f32 v[92:93], v[34:35], v[96:97]
	v_pk_mul_f32 v[90:91], v[8:9], v[90:91]
	v_pk_mul_f32 v[92:93], v[10:11], v[92:93]
	v_add_f32_e32 v90, v90, v91
	v_add_f32_e32 v91, v92, v93
	ds_read_b128 v[20:23], v114 offset:7936
	v_add_f32_e32 v90, v90, v91
	v_add_f32_dpp v42, v42, v42 quad_perm:[1,0,3,2] row_mask:0xf bank_mask:0xf bound_ctrl:1
	s_nop 0
	v_add_f32_dpp v90, v90, v90 quad_perm:[1,0,3,2] row_mask:0xf bank_mask:0xf bound_ctrl:1
	v_add_f32_dpp v42, v42, v42 quad_perm:[2,3,0,1] row_mask:0xf bank_mask:0xf bound_ctrl:1
	s_nop 0
	v_add_f32_dpp v90, v90, v90 quad_perm:[2,3,0,1] row_mask:0xf bank_mask:0xf bound_ctrl:1
	v_add_f32_dpp v42, v42, v42 row_half_mirror row_mask:0xf bank_mask:0xf bound_ctrl:1
	s_nop 0
	v_add_f32_dpp v90, v90, v90 row_half_mirror row_mask:0xf bank_mask:0xf bound_ctrl:1
	v_mov_b32_dpp v116, v42 row_mirror row_mask:0xf bank_mask:0xf bound_ctrl:1
	s_nop 0
	v_mov_b32_dpp v91, v90 row_mirror row_mask:0xf bank_mask:0xf bound_ctrl:1
	s_and_saveexec_b64 s[12:13], s[6:7]
	s_cbranch_execz .LBB0_419
	s_add_i32 s50, s94, 16
	v_cmp_lt_u32_e32 vcc, s50, v106
	s_and_b64 exec, exec, vcc
	s_cbranch_execz .LBB0_419
	v_add_f32_e32 v92, v90, v91
	v_add_u32_e32 v90, s50, v46
	v_ashrrev_i32_e32 v91, 31, v90
	v_lshlrev_b64 v[90:91], 6, v[90:91]
	v_lshl_add_u64 v[90:91], s[58:59], 0, v[90:91]
	global_store_dword v[90:91], v92, off

.LBB0_426:
	v_swap_b32 v29, v34
	v_swap_b32 v33, v90
	s_waitcnt lgkmcnt(0)
	v_pk_mul_f32 v[134:135], v[28:29], v[24:25] op_sel_hi:[1,0]
	v_pk_fma_f32 v[134:135], v[34:35], v[24:25], v[134:135] op_sel:[0,1,0]
	v_pk_fma_f32 v[134:135], v[32:33], v[26:27], v[134:135] op_sel_hi:[1,0,1]
	v_pk_fma_f32 v[134:135], v[90:91], v[26:27], v[134:135] op_sel:[0,1,0]
	v_pk_fma_f32 v[28:29], v[20:21], v[30:31], v[28:29] op_sel_hi:[0,1,1]
	v_pk_fma_f32 v[34:35], v[20:21], v[30:31], v[34:35] op_sel:[1,0,0]
	v_add_f32_dpp v134, v134, v134 quad_perm:[1,0,3,2] row_mask:0xf bank_mask:0xf bound_ctrl:1
	v_add_f32_dpp v135, v135, v135 quad_perm:[1,0,3,2] row_mask:0xf bank_mask:0xf bound_ctrl:1
	v_pk_fma_f32 v[32:33], v[22:23], v[30:31], v[32:33] op_sel_hi:[0,1,1]
	v_add_f32_dpp v134, v134, v134 quad_perm:[2,3,0,1] row_mask:0xf bank_mask:0xf bound_ctrl:1
	v_add_f32_dpp v135, v135, v135 quad_perm:[2,3,0,1] row_mask:0xf bank_mask:0xf bound_ctrl:1
	v_pk_fma_f32 v[90:91], v[22:23], v[30:31], v[90:91] op_sel:[1,0,0]
	v_add_f32_dpp v134, v134, v134 row_half_mirror row_mask:0xf bank_mask:0xf bound_ctrl:1
	v_add_f32_dpp v135, v135, v135 row_half_mirror row_mask:0xf bank_mask:0xf bound_ctrl:1
	ds_read_b128 v[116:119], v93 offset:12288
	ds_read_b128 v[120:123], v93 offset:16384
	ds_read_b128 v[124:127], v93 offset:8192
	ds_read_b128 v[130:133], v93
	ds_read_b64 v[96:97], v92
	v_add_f32_dpp v134, v134, v134 row_mirror row_mask:0xf bank_mask:0xf bound_ctrl:1
	v_add_f32_dpp v135, v135, v135 row_mirror row_mask:0xf bank_mask:0xf bound_ctrl:1
	v_pk_fma_f32 v[28:29], v[16:17], v[134:135], v[28:29] op_sel_hi:[0,1,1]
	v_pk_fma_f32 v[34:35], v[16:17], v[134:135], v[34:35] op_sel:[1,0,0]
	v_pk_fma_f32 v[32:33], v[18:19], v[134:135], v[32:33] op_sel_hi:[0,1,1]
	v_pk_fma_f32 v[90:91], v[18:19], v[134:135], v[90:91] op_sel:[1,0,0]
	s_waitcnt lgkmcnt(4)
	v_pk_mul_f32 v[134:135], v[28:29], v[116:117] op_sel_hi:[1,0]
	v_pk_mul_f32 v[16:17], v[28:29], v[12:13] op_sel_hi:[1,0]
	v_pk_fma_f32 v[134:135], v[34:35], v[116:117], v[134:135] op_sel:[0,1,0]
	v_pk_fma_f32 v[16:17], v[34:35], v[12:13], v[16:17] op_sel:[0,1,0]
	v_pk_fma_f32 v[134:135], v[32:33], v[118:119], v[134:135] op_sel_hi:[1,0,1]
	v_pk_fma_f32 v[16:17], v[32:33], v[14:15], v[16:17] op_sel_hi:[1,0,1]
	v_pk_fma_f32 v[134:135], v[90:91], v[118:119], v[134:135] op_sel:[0,1,0]
	v_pk_fma_f32 v[16:17], v[90:91], v[14:15], v[16:17] op_sel:[0,1,0]
	v_cvt_pk_f16_f32 v16, v16, v17
	v_add_f32_dpp v134, v134, v134 quad_perm:[1,0,3,2] row_mask:0xf bank_mask:0xf bound_ctrl:1
	v_add_f32_dpp v135, v135, v135 quad_perm:[1,0,3,2] row_mask:0xf bank_mask:0xf bound_ctrl:1
	ds_write_b32 v42, v16
	ds_read_b128 v[24:27], v94 offset:12800
	ds_read_b128 v[16:19], v94 offset:16896
	ds_read_b128 v[20:23], v94 offset:8704
	ds_read_b128 v[12:15], v94 offset:512
	s_waitcnt lgkmcnt(5)
	v_pk_fma_f32 v[28:29], v[124:125], v[96:97], v[28:29] op_sel_hi:[0,1,1]
	v_add_f32_dpp v134, v134, v134 quad_perm:[2,3,0,1] row_mask:0xf bank_mask:0xf bound_ctrl:1
	v_add_f32_dpp v135, v135, v135 quad_perm:[2,3,0,1] row_mask:0xf bank_mask:0xf bound_ctrl:1
	v_pk_fma_f32 v[34:35], v[124:125], v[96:97], v[34:35] op_sel:[1,0,0]
	v_add_f32_dpp v134, v134, v134 row_half_mirror row_mask:0xf bank_mask:0xf bound_ctrl:1
	v_add_f32_dpp v135, v135, v135 row_half_mirror row_mask:0xf bank_mask:0xf bound_ctrl:1
	v_pk_fma_f32 v[32:33], v[126:127], v[96:97], v[32:33] op_sel_hi:[0,1,1]
	v_pk_fma_f32 v[90:91], v[126:127], v[96:97], v[90:91] op_sel:[1,0,0]
	v_add_f32_dpp v134, v134, v134 row_mirror row_mask:0xf bank_mask:0xf bound_ctrl:1
	v_add_f32_dpp v135, v135, v135 row_mirror row_mask:0xf bank_mask:0xf bound_ctrl:1
	v_pk_fma_f32 v[28:29], v[120:121], v[134:135], v[28:29] op_sel_hi:[0,1,1]
	v_pk_fma_f32 v[34:35], v[120:121], v[134:135], v[34:35] op_sel:[1,0,0]
	v_pk_fma_f32 v[32:33], v[122:123], v[134:135], v[32:33] op_sel_hi:[0,1,1]
	v_pk_fma_f32 v[90:91], v[122:123], v[134:135], v[90:91] op_sel:[1,0,0]
	ds_read_b64 v[30:31], v95 offset:20736
	v_pk_mul_f32 v[116:117], v[28:29], v[130:131] op_sel_hi:[1,0]
	v_pk_fma_f32 v[116:117], v[34:35], v[130:131], v[116:117] op_sel:[0,1,0]
	v_pk_fma_f32 v[116:117], v[32:33], v[132:133], v[116:117] op_sel_hi:[1,0,1]
	v_pk_fma_f32 v[116:117], v[90:91], v[132:133], v[116:117] op_sel:[0,1,0]
	v_cvt_pk_f16_f32 v116, v116, v117
	ds_write_b32 v42, v116 offset:1024
	s_waitcnt lgkmcnt(0)
	v_pk_mul_f32 v[134:135], v[28:29], v[24:25] op_sel_hi:[1,0]
	v_pk_fma_f32 v[134:135], v[34:35], v[24:25], v[134:135] op_sel:[0,1,0]
	v_pk_fma_f32 v[134:135], v[32:33], v[26:27], v[134:135] op_sel_hi:[1,0,1]
	v_pk_fma_f32 v[134:135], v[90:91], v[26:27], v[134:135] op_sel:[0,1,0]
	v_pk_fma_f32 v[28:29], v[20:21], v[30:31], v[28:29] op_sel_hi:[0,1,1]
	v_pk_fma_f32 v[34:35], v[20:21], v[30:31], v[34:35] op_sel:[1,0,0]
	v_add_f32_dpp v134, v134, v134 quad_perm:[1,0,3,2] row_mask:0xf bank_mask:0xf bound_ctrl:1
	v_add_f32_dpp v135, v135, v135 quad_perm:[1,0,3,2] row_mask:0xf bank_mask:0xf bound_ctrl:1
	v_pk_fma_f32 v[32:33], v[22:23], v[30:31], v[32:33] op_sel_hi:[0,1,1]
	v_add_f32_dpp v134, v134, v134 quad_perm:[2,3,0,1] row_mask:0xf bank_mask:0xf bound_ctrl:1
	v_add_f32_dpp v135, v135, v135 quad_perm:[2,3,0,1] row_mask:0xf bank_mask:0xf bound_ctrl:1
	v_pk_fma_f32 v[90:91], v[22:23], v[30:31], v[90:91] op_sel:[1,0,0]
	v_add_f32_dpp v134, v134, v134 row_half_mirror row_mask:0xf bank_mask:0xf bound_ctrl:1
	v_add_f32_dpp v135, v135, v135 row_half_mirror row_mask:0xf bank_mask:0xf bound_ctrl:1
	ds_read_b128 v[116:119], v93 offset:12800
	ds_read_b128 v[120:123], v93 offset:16896
	ds_read_b128 v[124:127], v93 offset:8704
	ds_read_b128 v[130:133], v93 offset:512
	ds_read_b64 v[96:97], v92 offset:256
	v_add_f32_dpp v134, v134, v134 row_mirror row_mask:0xf bank_mask:0xf bound_ctrl:1
	v_add_f32_dpp v135, v135, v135 row_mirror row_mask:0xf bank_mask:0xf bound_ctrl:1
	v_pk_fma_f32 v[28:29], v[16:17], v[134:135], v[28:29] op_sel_hi:[0,1,1]
	v_pk_fma_f32 v[34:35], v[16:17], v[134:135], v[34:35] op_sel:[1,0,0]
	v_pk_fma_f32 v[32:33], v[18:19], v[134:135], v[32:33] op_sel_hi:[0,1,1]
	v_pk_fma_f32 v[90:91], v[18:19], v[134:135], v[90:91] op_sel:[1,0,0]
	s_waitcnt lgkmcnt(4)
	v_pk_mul_f32 v[134:135], v[28:29], v[116:117] op_sel_hi:[1,0]
	v_pk_mul_f32 v[16:17], v[28:29], v[12:13] op_sel_hi:[1,0]
	v_pk_fma_f32 v[134:135], v[34:35], v[116:117], v[134:135] op_sel:[0,1,0]
	v_pk_fma_f32 v[16:17], v[34:35], v[12:13], v[16:17] op_sel:[0,1,0]
	v_pk_fma_f32 v[134:135], v[32:33], v[118:119], v[134:135] op_sel_hi:[1,0,1]
	v_pk_fma_f32 v[16:17], v[32:33], v[14:15], v[16:17] op_sel_hi:[1,0,1]
	v_pk_fma_f32 v[134:135], v[90:91], v[118:119], v[134:135] op_sel:[0,1,0]
	v_pk_fma_f32 v[16:17], v[90:91], v[14:15], v[16:17] op_sel:[0,1,0]
	v_cvt_pk_f16_f32 v16, v16, v17
	v_add_f32_dpp v134, v134, v134 quad_perm:[1,0,3,2] row_mask:0xf bank_mask:0xf bound_ctrl:1
	v_add_f32_dpp v135, v135, v135 quad_perm:[1,0,3,2] row_mask:0xf bank_mask:0xf bound_ctrl:1
	ds_write_b32 v42, v16 offset:2048
	ds_read_b128 v[24:27], v94 offset:13312
	ds_read_b128 v[16:19], v94 offset:17408
	ds_read_b128 v[20:23], v94 offset:9216
	ds_read_b128 v[12:15], v94 offset:1024
	s_waitcnt lgkmcnt(5)
	v_pk_fma_f32 v[28:29], v[124:125], v[96:97], v[28:29] op_sel_hi:[0,1,1]
	v_add_f32_dpp v134, v134, v134 quad_perm:[2,3,0,1] row_mask:0xf bank_mask:0xf bound_ctrl:1
	v_add_f32_dpp v135, v135, v135 quad_perm:[2,3,0,1] row_mask:0xf bank_mask:0xf bound_ctrl:1
	v_pk_fma_f32 v[34:35], v[124:125], v[96:97], v[34:35] op_sel:[1,0,0]
	v_add_f32_dpp v134, v134, v134 row_half_mirror row_mask:0xf bank_mask:0xf bound_ctrl:1
	v_add_f32_dpp v135, v135, v135 row_half_mirror row_mask:0xf bank_mask:0xf bound_ctrl:1
	v_pk_fma_f32 v[32:33], v[126:127], v[96:97], v[32:33] op_sel_hi:[0,1,1]
	v_pk_fma_f32 v[90:91], v[126:127], v[96:97], v[90:91] op_sel:[1,0,0]
	v_add_f32_dpp v134, v134, v134 row_mirror row_mask:0xf bank_mask:0xf bound_ctrl:1
	v_add_f32_dpp v135, v135, v135 row_mirror row_mask:0xf bank_mask:0xf bound_ctrl:1
	v_pk_fma_f32 v[28:29], v[120:121], v[134:135], v[28:29] op_sel_hi:[0,1,1]
	v_pk_fma_f32 v[34:35], v[120:121], v[134:135], v[34:35] op_sel:[1,0,0]
	v_pk_fma_f32 v[32:33], v[122:123], v[134:135], v[32:33] op_sel_hi:[0,1,1]
	v_pk_fma_f32 v[90:91], v[122:123], v[134:135], v[90:91] op_sel:[1,0,0]
	ds_read_b64 v[30:31], v95 offset:20992
	v_pk_mul_f32 v[116:117], v[28:29], v[130:131] op_sel_hi:[1,0]
	v_pk_fma_f32 v[116:117], v[34:35], v[130:131], v[116:117] op_sel:[0,1,0]
	v_pk_fma_f32 v[116:117], v[32:33], v[132:133], v[116:117] op_sel_hi:[1,0,1]
	v_pk_fma_f32 v[116:117], v[90:91], v[132:133], v[116:117] op_sel:[0,1,0]
	v_cvt_pk_f16_f32 v116, v116, v117
	ds_write_b32 v42, v116 offset:3072
	s_waitcnt lgkmcnt(0)
	v_pk_mul_f32 v[134:135], v[28:29], v[24:25] op_sel_hi:[1,0]
	v_pk_fma_f32 v[134:135], v[34:35], v[24:25], v[134:135] op_sel:[0,1,0]
	v_pk_fma_f32 v[134:135], v[32:33], v[26:27], v[134:135] op_sel_hi:[1,0,1]
	v_pk_fma_f32 v[134:135], v[90:91], v[26:27], v[134:135] op_sel:[0,1,0]
	v_pk_fma_f32 v[28:29], v[20:21], v[30:31], v[28:29] op_sel_hi:[0,1,1]
	v_pk_fma_f32 v[34:35], v[20:21], v[30:31], v[34:35] op_sel:[1,0,0]
	v_add_f32_dpp v134, v134, v134 quad_perm:[1,0,3,2] row_mask:0xf bank_mask:0xf bound_ctrl:1
	v_add_f32_dpp v135, v135, v135 quad_perm:[1,0,3,2] row_mask:0xf bank_mask:0xf bound_ctrl:1
	v_pk_fma_f32 v[32:33], v[22:23], v[30:31], v[32:33] op_sel_hi:[0,1,1]
	v_add_f32_dpp v134, v134, v134 quad_perm:[2,3,0,1] row_mask:0xf bank_mask:0xf bound_ctrl:1
	v_add_f32_dpp v135, v135, v135 quad_perm:[2,3,0,1] row_mask:0xf bank_mask:0xf bound_ctrl:1
	v_pk_fma_f32 v[90:91], v[22:23], v[30:31], v[90:91] op_sel:[1,0,0]
	v_add_f32_dpp v134, v134, v134 row_half_mirror row_mask:0xf bank_mask:0xf bound_ctrl:1
	v_add_f32_dpp v135, v135, v135 row_half_mirror row_mask:0xf bank_mask:0xf bound_ctrl:1
	ds_read_b128 v[116:119], v93 offset:13312
	ds_read_b128 v[120:123], v93 offset:17408
	ds_read_b128 v[124:127], v93 offset:9216
	ds_read_b128 v[130:133], v93 offset:1024
	ds_read_b64 v[96:97], v92 offset:512
	v_add_f32_dpp v134, v134, v134 row_mirror row_mask:0xf bank_mask:0xf bound_ctrl:1
	v_add_f32_dpp v135, v135, v135 row_mirror row_mask:0xf bank_mask:0xf bound_ctrl:1
	v_pk_fma_f32 v[28:29], v[16:17], v[134:135], v[28:29] op_sel_hi:[0,1,1]
	v_pk_fma_f32 v[34:35], v[16:17], v[134:135], v[34:35] op_sel:[1,0,0]
	v_pk_fma_f32 v[32:33], v[18:19], v[134:135], v[32:33] op_sel_hi:[0,1,1]
	v_pk_fma_f32 v[90:91], v[18:19], v[134:135], v[90:91] op_sel:[1,0,0]
	s_waitcnt lgkmcnt(4)
	v_pk_mul_f32 v[134:135], v[28:29], v[116:117] op_sel_hi:[1,0]
	v_pk_mul_f32 v[16:17], v[28:29], v[12:13] op_sel_hi:[1,0]
	v_pk_fma_f32 v[134:135], v[34:35], v[116:117], v[134:135] op_sel:[0,1,0]
	v_pk_fma_f32 v[16:17], v[34:35], v[12:13], v[16:17] op_sel:[0,1,0]
	v_pk_fma_f32 v[134:135], v[32:33], v[118:119], v[134:135] op_sel_hi:[1,0,1]
	v_pk_fma_f32 v[16:17], v[32:33], v[14:15], v[16:17] op_sel_hi:[1,0,1]
	v_pk_fma_f32 v[134:135], v[90:91], v[118:119], v[134:135] op_sel:[0,1,0]
	v_pk_fma_f32 v[16:17], v[90:91], v[14:15], v[16:17] op_sel:[0,1,0]
	v_cvt_pk_f16_f32 v16, v16, v17
	v_add_f32_dpp v134, v134, v134 quad_perm:[1,0,3,2] row_mask:0xf bank_mask:0xf bound_ctrl:1
	v_add_f32_dpp v135, v135, v135 quad_perm:[1,0,3,2] row_mask:0xf bank_mask:0xf bound_ctrl:1
	ds_write_b32 v42, v16 offset:4096
	ds_read_b128 v[24:27], v94 offset:13824
	ds_read_b128 v[16:19], v94 offset:17920
	ds_read_b128 v[20:23], v94 offset:9728
	ds_read_b128 v[12:15], v94 offset:1536
	s_waitcnt lgkmcnt(5)
	v_pk_fma_f32 v[28:29], v[124:125], v[96:97], v[28:29] op_sel_hi:[0,1,1]
	v_add_f32_dpp v134, v134, v134 quad_perm:[2,3,0,1] row_mask:0xf bank_mask:0xf bound_ctrl:1
	v_add_f32_dpp v135, v135, v135 quad_perm:[2,3,0,1] row_mask:0xf bank_mask:0xf bound_ctrl:1
	v_pk_fma_f32 v[34:35], v[124:125], v[96:97], v[34:35] op_sel:[1,0,0]
	v_add_f32_dpp v134, v134, v134 row_half_mirror row_mask:0xf bank_mask:0xf bound_ctrl:1
	v_add_f32_dpp v135, v135, v135 row_half_mirror row_mask:0xf bank_mask:0xf bound_ctrl:1
	v_pk_fma_f32 v[32:33], v[126:127], v[96:97], v[32:33] op_sel_hi:[0,1,1]
	v_pk_fma_f32 v[90:91], v[126:127], v[96:97], v[90:91] op_sel:[1,0,0]
	v_add_f32_dpp v134, v134, v134 row_mirror row_mask:0xf bank_mask:0xf bound_ctrl:1
	v_add_f32_dpp v135, v135, v135 row_mirror row_mask:0xf bank_mask:0xf bound_ctrl:1
	v_pk_fma_f32 v[28:29], v[120:121], v[134:135], v[28:29] op_sel_hi:[0,1,1]
	v_pk_fma_f32 v[34:35], v[120:121], v[134:135], v[34:35] op_sel:[1,0,0]
	v_pk_fma_f32 v[32:33], v[122:123], v[134:135], v[32:33] op_sel_hi:[0,1,1]
	v_pk_fma_f32 v[90:91], v[122:123], v[134:135], v[90:91] op_sel:[1,0,0]
	ds_read_b64 v[30:31], v95 offset:21248
	v_pk_mul_f32 v[116:117], v[28:29], v[130:131] op_sel_hi:[1,0]
	v_pk_fma_f32 v[116:117], v[34:35], v[130:131], v[116:117] op_sel:[0,1,0]
	v_pk_fma_f32 v[116:117], v[32:33], v[132:133], v[116:117] op_sel_hi:[1,0,1]
	v_pk_fma_f32 v[116:117], v[90:91], v[132:133], v[116:117] op_sel:[0,1,0]
	v_cvt_pk_f16_f32 v116, v116, v117
	ds_write_b32 v42, v116 offset:5120
	s_waitcnt lgkmcnt(0)
	v_pk_mul_f32 v[134:135], v[28:29], v[24:25] op_sel_hi:[1,0]
	v_pk_fma_f32 v[134:135], v[34:35], v[24:25], v[134:135] op_sel:[0,1,0]
	v_pk_fma_f32 v[134:135], v[32:33], v[26:27], v[134:135] op_sel_hi:[1,0,1]
	v_pk_fma_f32 v[134:135], v[90:91], v[26:27], v[134:135] op_sel:[0,1,0]
	v_pk_fma_f32 v[28:29], v[20:21], v[30:31], v[28:29] op_sel_hi:[0,1,1]
	v_pk_fma_f32 v[34:35], v[20:21], v[30:31], v[34:35] op_sel:[1,0,0]
	v_add_f32_dpp v134, v134, v134 quad_perm:[1,0,3,2] row_mask:0xf bank_mask:0xf bound_ctrl:1
	v_add_f32_dpp v135, v135, v135 quad_perm:[1,0,3,2] row_mask:0xf bank_mask:0xf bound_ctrl:1
	v_pk_fma_f32 v[32:33], v[22:23], v[30:31], v[32:33] op_sel_hi:[0,1,1]
	v_add_f32_dpp v134, v134, v134 quad_perm:[2,3,0,1] row_mask:0xf bank_mask:0xf bound_ctrl:1
	v_add_f32_dpp v135, v135, v135 quad_perm:[2,3,0,1] row_mask:0xf bank_mask:0xf bound_ctrl:1
	v_pk_fma_f32 v[90:91], v[22:23], v[30:31], v[90:91] op_sel:[1,0,0]
	v_add_f32_dpp v134, v134, v134 row_half_mirror row_mask:0xf bank_mask:0xf bound_ctrl:1
	v_add_f32_dpp v135, v135, v135 row_half_mirror row_mask:0xf bank_mask:0xf bound_ctrl:1
	ds_read_b128 v[116:119], v93 offset:13824
	ds_read_b128 v[120:123], v93 offset:17920
	ds_read_b128 v[124:127], v93 offset:9728
	ds_read_b128 v[130:133], v93 offset:1536
	ds_read_b64 v[96:97], v92 offset:768
	v_add_f32_dpp v134, v134, v134 row_mirror row_mask:0xf bank_mask:0xf bound_ctrl:1
	v_add_f32_dpp v135, v135, v135 row_mirror row_mask:0xf bank_mask:0xf bound_ctrl:1
	v_pk_fma_f32 v[28:29], v[16:17], v[134:135], v[28:29] op_sel_hi:[0,1,1]
	v_pk_fma_f32 v[34:35], v[16:17], v[134:135], v[34:35] op_sel:[1,0,0]
	v_pk_fma_f32 v[32:33], v[18:19], v[134:135], v[32:33] op_sel_hi:[0,1,1]
	v_pk_fma_f32 v[90:91], v[18:19], v[134:135], v[90:91] op_sel:[1,0,0]
	s_waitcnt lgkmcnt(4)
	v_pk_mul_f32 v[134:135], v[28:29], v[116:117] op_sel_hi:[1,0]
	v_pk_mul_f32 v[16:17], v[28:29], v[12:13] op_sel_hi:[1,0]
	v_pk_fma_f32 v[134:135], v[34:35], v[116:117], v[134:135] op_sel:[0,1,0]
	v_pk_fma_f32 v[16:17], v[34:35], v[12:13], v[16:17] op_sel:[0,1,0]
	v_pk_fma_f32 v[134:135], v[32:33], v[118:119], v[134:135] op_sel_hi:[1,0,1]
	v_pk_fma_f32 v[16:17], v[32:33], v[14:15], v[16:17] op_sel_hi:[1,0,1]
	v_pk_fma_f32 v[134:135], v[90:91], v[118:119], v[134:135] op_sel:[0,1,0]
	v_pk_fma_f32 v[16:17], v[90:91], v[14:15], v[16:17] op_sel:[0,1,0]
	v_cvt_pk_f16_f32 v16, v16, v17
	v_add_f32_dpp v134, v134, v134 quad_perm:[1,0,3,2] row_mask:0xf bank_mask:0xf bound_ctrl:1
	v_add_f32_dpp v135, v135, v135 quad_perm:[1,0,3,2] row_mask:0xf bank_mask:0xf bound_ctrl:1
	ds_write_b32 v42, v16 offset:6144
	ds_read_b128 v[24:27], v94 offset:14336
	ds_read_b128 v[16:19], v94 offset:18432
	ds_read_b128 v[20:23], v94 offset:10240
	ds_read_b128 v[12:15], v94 offset:2048
	s_waitcnt lgkmcnt(5)
	v_pk_fma_f32 v[28:29], v[124:125], v[96:97], v[28:29] op_sel_hi:[0,1,1]
	v_add_f32_dpp v134, v134, v134 quad_perm:[2,3,0,1] row_mask:0xf bank_mask:0xf bound_ctrl:1
	v_add_f32_dpp v135, v135, v135 quad_perm:[2,3,0,1] row_mask:0xf bank_mask:0xf bound_ctrl:1
	v_pk_fma_f32 v[34:35], v[124:125], v[96:97], v[34:35] op_sel:[1,0,0]
	v_add_f32_dpp v134, v134, v134 row_half_mirror row_mask:0xf bank_mask:0xf bound_ctrl:1
	v_add_f32_dpp v135, v135, v135 row_half_mirror row_mask:0xf bank_mask:0xf bound_ctrl:1
	v_pk_fma_f32 v[32:33], v[126:127], v[96:97], v[32:33] op_sel_hi:[0,1,1]
	v_pk_fma_f32 v[90:91], v[126:127], v[96:97], v[90:91] op_sel:[1,0,0]
	v_add_f32_dpp v134, v134, v134 row_mirror row_mask:0xf bank_mask:0xf bound_ctrl:1
	v_add_f32_dpp v135, v135, v135 row_mirror row_mask:0xf bank_mask:0xf bound_ctrl:1
	v_pk_fma_f32 v[28:29], v[120:121], v[134:135], v[28:29] op_sel_hi:[0,1,1]
	v_pk_fma_f32 v[34:35], v[120:121], v[134:135], v[34:35] op_sel:[1,0,0]
	v_pk_fma_f32 v[32:33], v[122:123], v[134:135], v[32:33] op_sel_hi:[0,1,1]
	v_pk_fma_f32 v[90:91], v[122:123], v[134:135], v[90:91] op_sel:[1,0,0]
	ds_read_b64 v[30:31], v95 offset:21504
	v_pk_mul_f32 v[116:117], v[28:29], v[130:131] op_sel_hi:[1,0]
	v_pk_fma_f32 v[116:117], v[34:35], v[130:131], v[116:117] op_sel:[0,1,0]
	v_pk_fma_f32 v[116:117], v[32:33], v[132:133], v[116:117] op_sel_hi:[1,0,1]
	v_pk_fma_f32 v[116:117], v[90:91], v[132:133], v[116:117] op_sel:[0,1,0]
	v_cvt_pk_f16_f32 v116, v116, v117
	ds_write_b32 v42, v116 offset:7168
	s_waitcnt lgkmcnt(0)
	v_pk_mul_f32 v[134:135], v[28:29], v[24:25] op_sel_hi:[1,0]
	v_pk_fma_f32 v[134:135], v[34:35], v[24:25], v[134:135] op_sel:[0,1,0]
	v_pk_fma_f32 v[134:135], v[32:33], v[26:27], v[134:135] op_sel_hi:[1,0,1]
	v_pk_fma_f32 v[134:135], v[90:91], v[26:27], v[134:135] op_sel:[0,1,0]
	v_pk_fma_f32 v[28:29], v[20:21], v[30:31], v[28:29] op_sel_hi:[0,1,1]
	v_pk_fma_f32 v[34:35], v[20:21], v[30:31], v[34:35] op_sel:[1,0,0]
	v_add_f32_dpp v134, v134, v134 quad_perm:[1,0,3,2] row_mask:0xf bank_mask:0xf bound_ctrl:1
	v_add_f32_dpp v135, v135, v135 quad_perm:[1,0,3,2] row_mask:0xf bank_mask:0xf bound_ctrl:1
	v_pk_fma_f32 v[32:33], v[22:23], v[30:31], v[32:33] op_sel_hi:[0,1,1]
	v_add_f32_dpp v134, v134, v134 quad_perm:[2,3,0,1] row_mask:0xf bank_mask:0xf bound_ctrl:1
	v_add_f32_dpp v135, v135, v135 quad_perm:[2,3,0,1] row_mask:0xf bank_mask:0xf bound_ctrl:1
	v_pk_fma_f32 v[90:91], v[22:23], v[30:31], v[90:91] op_sel:[1,0,0]
	v_add_f32_dpp v134, v134, v134 row_half_mirror row_mask:0xf bank_mask:0xf bound_ctrl:1
	v_add_f32_dpp v135, v135, v135 row_half_mirror row_mask:0xf bank_mask:0xf bound_ctrl:1
	ds_read_b128 v[116:119], v93 offset:14336
	ds_read_b128 v[120:123], v93 offset:18432
	ds_read_b128 v[124:127], v93 offset:10240
	ds_read_b128 v[130:133], v93 offset:2048
	ds_read_b64 v[96:97], v92 offset:1024
	v_add_f32_dpp v134, v134, v134 row_mirror row_mask:0xf bank_mask:0xf bound_ctrl:1
	v_add_f32_dpp v135, v135, v135 row_mirror row_mask:0xf bank_mask:0xf bound_ctrl:1
	v_pk_fma_f32 v[28:29], v[16:17], v[134:135], v[28:29] op_sel_hi:[0,1,1]
	v_pk_fma_f32 v[34:35], v[16:17], v[134:135], v[34:35] op_sel:[1,0,0]
	v_pk_fma_f32 v[32:33], v[18:19], v[134:135], v[32:33] op_sel_hi:[0,1,1]
	v_pk_fma_f32 v[90:91], v[18:19], v[134:135], v[90:91] op_sel:[1,0,0]
	s_waitcnt lgkmcnt(4)
	v_pk_mul_f32 v[134:135], v[28:29], v[116:117] op_sel_hi:[1,0]
	v_pk_mul_f32 v[16:17], v[28:29], v[12:13] op_sel_hi:[1,0]
	v_pk_fma_f32 v[134:135], v[34:35], v[116:117], v[134:135] op_sel:[0,1,0]
	v_pk_fma_f32 v[16:17], v[34:35], v[12:13], v[16:17] op_sel:[0,1,0]
	v_pk_fma_f32 v[134:135], v[32:33], v[118:119], v[134:135] op_sel_hi:[1,0,1]
	v_pk_fma_f32 v[16:17], v[32:33], v[14:15], v[16:17] op_sel_hi:[1,0,1]
	v_pk_fma_f32 v[134:135], v[90:91], v[118:119], v[134:135] op_sel:[0,1,0]
	v_pk_fma_f32 v[16:17], v[90:91], v[14:15], v[16:17] op_sel:[0,1,0]
	v_cvt_pk_f16_f32 v16, v16, v17
	v_add_f32_dpp v134, v134, v134 quad_perm:[1,0,3,2] row_mask:0xf bank_mask:0xf bound_ctrl:1
	v_add_f32_dpp v135, v135, v135 quad_perm:[1,0,3,2] row_mask:0xf bank_mask:0xf bound_ctrl:1
	ds_write_b32 v42, v16 offset:8192
	ds_read_b128 v[24:27], v94 offset:14848
	ds_read_b128 v[16:19], v94 offset:18944
	ds_read_b128 v[20:23], v94 offset:10752
	ds_read_b128 v[12:15], v94 offset:2560
	s_waitcnt lgkmcnt(5)
	v_pk_fma_f32 v[28:29], v[124:125], v[96:97], v[28:29] op_sel_hi:[0,1,1]
	v_add_f32_dpp v134, v134, v134 quad_perm:[2,3,0,1] row_mask:0xf bank_mask:0xf bound_ctrl:1
	v_add_f32_dpp v135, v135, v135 quad_perm:[2,3,0,1] row_mask:0xf bank_mask:0xf bound_ctrl:1
	v_pk_fma_f32 v[34:35], v[124:125], v[96:97], v[34:35] op_sel:[1,0,0]
	v_add_f32_dpp v134, v134, v134 row_half_mirror row_mask:0xf bank_mask:0xf bound_ctrl:1
	v_add_f32_dpp v135, v135, v135 row_half_mirror row_mask:0xf bank_mask:0xf bound_ctrl:1
	v_pk_fma_f32 v[32:33], v[126:127], v[96:97], v[32:33] op_sel_hi:[0,1,1]
	v_pk_fma_f32 v[90:91], v[126:127], v[96:97], v[90:91] op_sel:[1,0,0]
	v_add_f32_dpp v134, v134, v134 row_mirror row_mask:0xf bank_mask:0xf bound_ctrl:1
	v_add_f32_dpp v135, v135, v135 row_mirror row_mask:0xf bank_mask:0xf bound_ctrl:1
	v_pk_fma_f32 v[28:29], v[120:121], v[134:135], v[28:29] op_sel_hi:[0,1,1]
	v_pk_fma_f32 v[34:35], v[120:121], v[134:135], v[34:35] op_sel:[1,0,0]
	v_pk_fma_f32 v[32:33], v[122:123], v[134:135], v[32:33] op_sel_hi:[0,1,1]
	v_pk_fma_f32 v[90:91], v[122:123], v[134:135], v[90:91] op_sel:[1,0,0]
	ds_read_b64 v[30:31], v95 offset:21760
	v_pk_mul_f32 v[116:117], v[28:29], v[130:131] op_sel_hi:[1,0]
	v_pk_fma_f32 v[116:117], v[34:35], v[130:131], v[116:117] op_sel:[0,1,0]
	v_pk_fma_f32 v[116:117], v[32:33], v[132:133], v[116:117] op_sel_hi:[1,0,1]
	v_pk_fma_f32 v[116:117], v[90:91], v[132:133], v[116:117] op_sel:[0,1,0]
	v_cvt_pk_f16_f32 v116, v116, v117
	ds_write_b32 v42, v116 offset:9216
	s_waitcnt lgkmcnt(0)
	v_pk_mul_f32 v[134:135], v[28:29], v[24:25] op_sel_hi:[1,0]
	v_pk_fma_f32 v[134:135], v[34:35], v[24:25], v[134:135] op_sel:[0,1,0]
	v_pk_fma_f32 v[134:135], v[32:33], v[26:27], v[134:135] op_sel_hi:[1,0,1]
	v_pk_fma_f32 v[134:135], v[90:91], v[26:27], v[134:135] op_sel:[0,1,0]
	v_pk_fma_f32 v[28:29], v[20:21], v[30:31], v[28:29] op_sel_hi:[0,1,1]
	v_pk_fma_f32 v[34:35], v[20:21], v[30:31], v[34:35] op_sel:[1,0,0]
	v_add_f32_dpp v134, v134, v134 quad_perm:[1,0,3,2] row_mask:0xf bank_mask:0xf bound_ctrl:1
	v_add_f32_dpp v135, v135, v135 quad_perm:[1,0,3,2] row_mask:0xf bank_mask:0xf bound_ctrl:1
	v_pk_fma_f32 v[32:33], v[22:23], v[30:31], v[32:33] op_sel_hi:[0,1,1]
	v_add_f32_dpp v134, v134, v134 quad_perm:[2,3,0,1] row_mask:0xf bank_mask:0xf bound_ctrl:1
	v_add_f32_dpp v135, v135, v135 quad_perm:[2,3,0,1] row_mask:0xf bank_mask:0xf bound_ctrl:1
	v_pk_fma_f32 v[90:91], v[22:23], v[30:31], v[90:91] op_sel:[1,0,0]
	v_add_f32_dpp v134, v134, v134 row_half_mirror row_mask:0xf bank_mask:0xf bound_ctrl:1
	v_add_f32_dpp v135, v135, v135 row_half_mirror row_mask:0xf bank_mask:0xf bound_ctrl:1
	ds_read_b128 v[116:119], v93 offset:14848
	ds_read_b128 v[120:123], v93 offset:18944
	ds_read_b128 v[124:127], v93 offset:10752
	ds_read_b128 v[130:133], v93 offset:2560
	ds_read_b64 v[96:97], v92 offset:1280
	v_add_f32_dpp v134, v134, v134 row_mirror row_mask:0xf bank_mask:0xf bound_ctrl:1
	v_add_f32_dpp v135, v135, v135 row_mirror row_mask:0xf bank_mask:0xf bound_ctrl:1
	v_pk_fma_f32 v[28:29], v[16:17], v[134:135], v[28:29] op_sel_hi:[0,1,1]
	v_pk_fma_f32 v[34:35], v[16:17], v[134:135], v[34:35] op_sel:[1,0,0]
	v_pk_fma_f32 v[32:33], v[18:19], v[134:135], v[32:33] op_sel_hi:[0,1,1]
	v_pk_fma_f32 v[90:91], v[18:19], v[134:135], v[90:91] op_sel:[1,0,0]
	s_waitcnt lgkmcnt(4)
	v_pk_mul_f32 v[134:135], v[28:29], v[116:117] op_sel_hi:[1,0]
	v_pk_mul_f32 v[16:17], v[28:29], v[12:13] op_sel_hi:[1,0]
	v_pk_fma_f32 v[134:135], v[34:35], v[116:117], v[134:135] op_sel:[0,1,0]
	v_pk_fma_f32 v[16:17], v[34:35], v[12:13], v[16:17] op_sel:[0,1,0]
	v_pk_fma_f32 v[134:135], v[32:33], v[118:119], v[134:135] op_sel_hi:[1,0,1]
	v_pk_fma_f32 v[16:17], v[32:33], v[14:15], v[16:17] op_sel_hi:[1,0,1]
	v_pk_fma_f32 v[134:135], v[90:91], v[118:119], v[134:135] op_sel:[0,1,0]
	v_pk_fma_f32 v[16:17], v[90:91], v[14:15], v[16:17] op_sel:[0,1,0]
	v_cvt_pk_f16_f32 v16, v16, v17
	v_add_f32_dpp v134, v134, v134 quad_perm:[1,0,3,2] row_mask:0xf bank_mask:0xf bound_ctrl:1
	v_add_f32_dpp v135, v135, v135 quad_perm:[1,0,3,2] row_mask:0xf bank_mask:0xf bound_ctrl:1
	ds_write_b32 v42, v16 offset:10240
	ds_read_b128 v[24:27], v94 offset:15360
	ds_read_b128 v[16:19], v94 offset:19456
	ds_read_b128 v[20:23], v94 offset:11264
	ds_read_b128 v[12:15], v94 offset:3072
	s_waitcnt lgkmcnt(5)
	v_pk_fma_f32 v[28:29], v[124:125], v[96:97], v[28:29] op_sel_hi:[0,1,1]
	v_add_f32_dpp v134, v134, v134 quad_perm:[2,3,0,1] row_mask:0xf bank_mask:0xf bound_ctrl:1
	v_add_f32_dpp v135, v135, v135 quad_perm:[2,3,0,1] row_mask:0xf bank_mask:0xf bound_ctrl:1
	v_pk_fma_f32 v[34:35], v[124:125], v[96:97], v[34:35] op_sel:[1,0,0]
	v_add_f32_dpp v134, v134, v134 row_half_mirror row_mask:0xf bank_mask:0xf bound_ctrl:1
	v_add_f32_dpp v135, v135, v135 row_half_mirror row_mask:0xf bank_mask:0xf bound_ctrl:1
	v_pk_fma_f32 v[32:33], v[126:127], v[96:97], v[32:33] op_sel_hi:[0,1,1]
	v_pk_fma_f32 v[90:91], v[126:127], v[96:97], v[90:91] op_sel:[1,0,0]
	v_add_f32_dpp v134, v134, v134 row_mirror row_mask:0xf bank_mask:0xf bound_ctrl:1
	v_add_f32_dpp v135, v135, v135 row_mirror row_mask:0xf bank_mask:0xf bound_ctrl:1
	v_pk_fma_f32 v[28:29], v[120:121], v[134:135], v[28:29] op_sel_hi:[0,1,1]
	v_pk_fma_f32 v[34:35], v[120:121], v[134:135], v[34:35] op_sel:[1,0,0]
	v_pk_fma_f32 v[32:33], v[122:123], v[134:135], v[32:33] op_sel_hi:[0,1,1]
	v_pk_fma_f32 v[90:91], v[122:123], v[134:135], v[90:91] op_sel:[1,0,0]
	ds_read_b64 v[30:31], v95 offset:22016
	v_pk_mul_f32 v[116:117], v[28:29], v[130:131] op_sel_hi:[1,0]
	v_pk_fma_f32 v[116:117], v[34:35], v[130:131], v[116:117] op_sel:[0,1,0]
	v_pk_fma_f32 v[116:117], v[32:33], v[132:133], v[116:117] op_sel_hi:[1,0,1]
	v_pk_fma_f32 v[116:117], v[90:91], v[132:133], v[116:117] op_sel:[0,1,0]
	v_cvt_pk_f16_f32 v116, v116, v117
	ds_write_b32 v42, v116 offset:11264
	s_waitcnt lgkmcnt(0)
	v_pk_mul_f32 v[134:135], v[28:29], v[24:25] op_sel_hi:[1,0]
	v_pk_fma_f32 v[134:135], v[34:35], v[24:25], v[134:135] op_sel:[0,1,0]
	v_pk_fma_f32 v[134:135], v[32:33], v[26:27], v[134:135] op_sel_hi:[1,0,1]
	v_pk_fma_f32 v[134:135], v[90:91], v[26:27], v[134:135] op_sel:[0,1,0]
	v_pk_fma_f32 v[28:29], v[20:21], v[30:31], v[28:29] op_sel_hi:[0,1,1]
	v_pk_fma_f32 v[34:35], v[20:21], v[30:31], v[34:35] op_sel:[1,0,0]
	v_add_f32_dpp v134, v134, v134 quad_perm:[1,0,3,2] row_mask:0xf bank_mask:0xf bound_ctrl:1
	v_add_f32_dpp v135, v135, v135 quad_perm:[1,0,3,2] row_mask:0xf bank_mask:0xf bound_ctrl:1
	v_pk_fma_f32 v[32:33], v[22:23], v[30:31], v[32:33] op_sel_hi:[0,1,1]
	v_add_f32_dpp v134, v134, v134 quad_perm:[2,3,0,1] row_mask:0xf bank_mask:0xf bound_ctrl:1
	v_add_f32_dpp v135, v135, v135 quad_perm:[2,3,0,1] row_mask:0xf bank_mask:0xf bound_ctrl:1
	v_pk_fma_f32 v[90:91], v[22:23], v[30:31], v[90:91] op_sel:[1,0,0]
	v_add_f32_dpp v134, v134, v134 row_half_mirror row_mask:0xf bank_mask:0xf bound_ctrl:1
	v_add_f32_dpp v135, v135, v135 row_half_mirror row_mask:0xf bank_mask:0xf bound_ctrl:1
	ds_read_b128 v[116:119], v93 offset:15360
	ds_read_b128 v[120:123], v93 offset:19456
	ds_read_b128 v[124:127], v93 offset:11264
	ds_read_b128 v[130:133], v93 offset:3072
	ds_read_b64 v[96:97], v92 offset:1536
	v_add_f32_dpp v134, v134, v134 row_mirror row_mask:0xf bank_mask:0xf bound_ctrl:1
	v_add_f32_dpp v135, v135, v135 row_mirror row_mask:0xf bank_mask:0xf bound_ctrl:1
	v_pk_fma_f32 v[28:29], v[16:17], v[134:135], v[28:29] op_sel_hi:[0,1,1]
	v_pk_fma_f32 v[34:35], v[16:17], v[134:135], v[34:35] op_sel:[1,0,0]
	v_pk_fma_f32 v[32:33], v[18:19], v[134:135], v[32:33] op_sel_hi:[0,1,1]
	v_pk_fma_f32 v[90:91], v[18:19], v[134:135], v[90:91] op_sel:[1,0,0]
	s_waitcnt lgkmcnt(4)
	v_pk_mul_f32 v[134:135], v[28:29], v[116:117] op_sel_hi:[1,0]
	v_pk_mul_f32 v[16:17], v[28:29], v[12:13] op_sel_hi:[1,0]
	v_pk_fma_f32 v[134:135], v[34:35], v[116:117], v[134:135] op_sel:[0,1,0]
	v_pk_fma_f32 v[16:17], v[34:35], v[12:13], v[16:17] op_sel:[0,1,0]
	v_pk_fma_f32 v[134:135], v[32:33], v[118:119], v[134:135] op_sel_hi:[1,0,1]
	v_pk_fma_f32 v[16:17], v[32:33], v[14:15], v[16:17] op_sel_hi:[1,0,1]
	v_pk_fma_f32 v[134:135], v[90:91], v[118:119], v[134:135] op_sel:[0,1,0]
	v_pk_fma_f32 v[16:17], v[90:91], v[14:15], v[16:17] op_sel:[0,1,0]
	v_cvt_pk_f16_f32 v16, v16, v17
	v_add_f32_dpp v134, v134, v134 quad_perm:[1,0,3,2] row_mask:0xf bank_mask:0xf bound_ctrl:1
	v_add_f32_dpp v135, v135, v135 quad_perm:[1,0,3,2] row_mask:0xf bank_mask:0xf bound_ctrl:1
	ds_write_b32 v42, v16 offset:12288
	ds_read_b128 v[24:27], v94 offset:15872
	ds_read_b128 v[16:19], v94 offset:19968
	ds_read_b128 v[20:23], v94 offset:11776
	ds_read_b128 v[12:15], v94 offset:3584
	s_waitcnt lgkmcnt(5)
	v_pk_fma_f32 v[28:29], v[124:125], v[96:97], v[28:29] op_sel_hi:[0,1,1]
	v_add_f32_dpp v134, v134, v134 quad_perm:[2,3,0,1] row_mask:0xf bank_mask:0xf bound_ctrl:1
	v_add_f32_dpp v135, v135, v135 quad_perm:[2,3,0,1] row_mask:0xf bank_mask:0xf bound_ctrl:1
	v_pk_fma_f32 v[34:35], v[124:125], v[96:97], v[34:35] op_sel:[1,0,0]
	v_add_f32_dpp v134, v134, v134 row_half_mirror row_mask:0xf bank_mask:0xf bound_ctrl:1
	v_add_f32_dpp v135, v135, v135 row_half_mirror row_mask:0xf bank_mask:0xf bound_ctrl:1
	v_pk_fma_f32 v[32:33], v[126:127], v[96:97], v[32:33] op_sel_hi:[0,1,1]
	v_pk_fma_f32 v[90:91], v[126:127], v[96:97], v[90:91] op_sel:[1,0,0]
	v_add_f32_dpp v134, v134, v134 row_mirror row_mask:0xf bank_mask:0xf bound_ctrl:1
	v_add_f32_dpp v135, v135, v135 row_mirror row_mask:0xf bank_mask:0xf bound_ctrl:1
	v_pk_fma_f32 v[28:29], v[120:121], v[134:135], v[28:29] op_sel_hi:[0,1,1]
	v_pk_fma_f32 v[34:35], v[120:121], v[134:135], v[34:35] op_sel:[1,0,0]
	v_pk_fma_f32 v[32:33], v[122:123], v[134:135], v[32:33] op_sel_hi:[0,1,1]
	v_pk_fma_f32 v[90:91], v[122:123], v[134:135], v[90:91] op_sel:[1,0,0]
	ds_read_b64 v[30:31], v95 offset:22272
	v_pk_mul_f32 v[116:117], v[28:29], v[130:131] op_sel_hi:[1,0]
	v_pk_fma_f32 v[116:117], v[34:35], v[130:131], v[116:117] op_sel:[0,1,0]
	v_pk_fma_f32 v[116:117], v[32:33], v[132:133], v[116:117] op_sel_hi:[1,0,1]
	v_pk_fma_f32 v[116:117], v[90:91], v[132:133], v[116:117] op_sel:[0,1,0]
	v_cvt_pk_f16_f32 v116, v116, v117
	ds_write_b32 v42, v116 offset:13312
	s_waitcnt lgkmcnt(0)
	v_pk_mul_f32 v[134:135], v[28:29], v[24:25] op_sel_hi:[1,0]
	v_pk_fma_f32 v[134:135], v[34:35], v[24:25], v[134:135] op_sel:[0,1,0]
	v_pk_fma_f32 v[134:135], v[32:33], v[26:27], v[134:135] op_sel_hi:[1,0,1]
	v_pk_fma_f32 v[134:135], v[90:91], v[26:27], v[134:135] op_sel:[0,1,0]
	v_pk_fma_f32 v[28:29], v[20:21], v[30:31], v[28:29] op_sel_hi:[0,1,1]
	v_pk_fma_f32 v[34:35], v[20:21], v[30:31], v[34:35] op_sel:[1,0,0]
	v_add_f32_dpp v134, v134, v134 quad_perm:[1,0,3,2] row_mask:0xf bank_mask:0xf bound_ctrl:1
	v_add_f32_dpp v135, v135, v135 quad_perm:[1,0,3,2] row_mask:0xf bank_mask:0xf bound_ctrl:1
	v_pk_fma_f32 v[32:33], v[22:23], v[30:31], v[32:33] op_sel_hi:[0,1,1]
	v_add_f32_dpp v134, v134, v134 quad_perm:[2,3,0,1] row_mask:0xf bank_mask:0xf bound_ctrl:1
	v_add_f32_dpp v135, v135, v135 quad_perm:[2,3,0,1] row_mask:0xf bank_mask:0xf bound_ctrl:1
	v_pk_fma_f32 v[90:91], v[22:23], v[30:31], v[90:91] op_sel:[1,0,0]
	v_add_f32_dpp v134, v134, v134 row_half_mirror row_mask:0xf bank_mask:0xf bound_ctrl:1
	v_add_f32_dpp v135, v135, v135 row_half_mirror row_mask:0xf bank_mask:0xf bound_ctrl:1
	ds_read_b128 v[116:119], v93 offset:15872
	ds_read_b128 v[120:123], v93 offset:19968
	ds_read_b128 v[124:127], v93 offset:11776
	ds_read_b128 v[130:133], v93 offset:3584
	ds_read_b64 v[96:97], v92 offset:1792
	v_add_f32_dpp v134, v134, v134 row_mirror row_mask:0xf bank_mask:0xf bound_ctrl:1
	v_add_f32_dpp v135, v135, v135 row_mirror row_mask:0xf bank_mask:0xf bound_ctrl:1
	v_pk_fma_f32 v[28:29], v[16:17], v[134:135], v[28:29] op_sel_hi:[0,1,1]
	v_pk_fma_f32 v[34:35], v[16:17], v[134:135], v[34:35] op_sel:[1,0,0]
	v_pk_fma_f32 v[32:33], v[18:19], v[134:135], v[32:33] op_sel_hi:[0,1,1]
	v_pk_fma_f32 v[90:91], v[18:19], v[134:135], v[90:91] op_sel:[1,0,0]
	s_waitcnt lgkmcnt(4)
	v_pk_mul_f32 v[134:135], v[28:29], v[116:117] op_sel_hi:[1,0]
	v_pk_mul_f32 v[16:17], v[28:29], v[12:13] op_sel_hi:[1,0]
	v_pk_fma_f32 v[134:135], v[34:35], v[116:117], v[134:135] op_sel:[0,1,0]
	v_pk_fma_f32 v[16:17], v[34:35], v[12:13], v[16:17] op_sel:[0,1,0]
	v_pk_fma_f32 v[134:135], v[32:33], v[118:119], v[134:135] op_sel_hi:[1,0,1]
	v_pk_fma_f32 v[16:17], v[32:33], v[14:15], v[16:17] op_sel_hi:[1,0,1]
	v_pk_fma_f32 v[134:135], v[90:91], v[118:119], v[134:135] op_sel:[0,1,0]
	v_pk_fma_f32 v[16:17], v[90:91], v[14:15], v[16:17] op_sel:[0,1,0]
	v_cvt_pk_f16_f32 v16, v16, v17
	v_add_f32_dpp v134, v134, v134 quad_perm:[1,0,3,2] row_mask:0xf bank_mask:0xf bound_ctrl:1
	v_add_f32_dpp v135, v135, v135 quad_perm:[1,0,3,2] row_mask:0xf bank_mask:0xf bound_ctrl:1
	ds_write_b32 v42, v16 offset:14336
	ds_read_b128 v[24:27], v94 offset:15872
	ds_read_b128 v[16:19], v94 offset:19968
	ds_read_b128 v[20:23], v94 offset:11776
	ds_read_b128 v[12:15], v94 offset:3584
	s_waitcnt lgkmcnt(5)
	v_pk_fma_f32 v[28:29], v[124:125], v[96:97], v[28:29] op_sel_hi:[0,1,1]
	v_add_f32_dpp v134, v134, v134 quad_perm:[2,3,0,1] row_mask:0xf bank_mask:0xf bound_ctrl:1
	v_add_f32_dpp v135, v135, v135 quad_perm:[2,3,0,1] row_mask:0xf bank_mask:0xf bound_ctrl:1
	v_pk_fma_f32 v[34:35], v[124:125], v[96:97], v[34:35] op_sel:[1,0,0]
	v_add_f32_dpp v134, v134, v134 row_half_mirror row_mask:0xf bank_mask:0xf bound_ctrl:1
	v_add_f32_dpp v135, v135, v135 row_half_mirror row_mask:0xf bank_mask:0xf bound_ctrl:1
	v_pk_fma_f32 v[32:33], v[126:127], v[96:97], v[32:33] op_sel_hi:[0,1,1]
	v_pk_fma_f32 v[90:91], v[126:127], v[96:97], v[90:91] op_sel:[1,0,0]
	v_add_f32_dpp v134, v134, v134 row_mirror row_mask:0xf bank_mask:0xf bound_ctrl:1
	v_add_f32_dpp v135, v135, v135 row_mirror row_mask:0xf bank_mask:0xf bound_ctrl:1
	v_pk_fma_f32 v[28:29], v[120:121], v[134:135], v[28:29] op_sel_hi:[0,1,1]
	v_pk_fma_f32 v[34:35], v[120:121], v[134:135], v[34:35] op_sel:[1,0,0]
	v_pk_fma_f32 v[32:33], v[122:123], v[134:135], v[32:33] op_sel_hi:[0,1,1]
	v_pk_fma_f32 v[90:91], v[122:123], v[134:135], v[90:91] op_sel:[1,0,0]
	ds_read_b64 v[30:31], v95 offset:22272
	v_pk_mul_f32 v[116:117], v[28:29], v[130:131] op_sel_hi:[1,0]
	v_pk_fma_f32 v[116:117], v[34:35], v[130:131], v[116:117] op_sel:[0,1,0]
	v_pk_fma_f32 v[116:117], v[32:33], v[132:133], v[116:117] op_sel_hi:[1,0,1]
	v_pk_fma_f32 v[116:117], v[90:91], v[132:133], v[116:117] op_sel:[0,1,0]
	v_cvt_pk_f16_f32 v116, v116, v117
	ds_write_b32 v42, v116 offset:15360
	v_swap_b32 v29, v34
	v_swap_b32 v33, v90
	s_waitcnt vmcnt(4) lgkmcnt(1)
	v_cvt_f32_f16_sdwa v31, v72 dst_sel:DWORD dst_unused:UNUSED_PAD src0_sel:WORD_1
	v_cvt_f32_f16_e32 v30, v72
	v_cvt_f32_f16_sdwa v93, v73 dst_sel:DWORD dst_unused:UNUSED_PAD src0_sel:WORD_1
	v_cvt_f32_f16_e32 v92, v73
	s_waitcnt vmcnt(1)
	v_cvt_f32_f16_sdwa v17, v80 dst_sel:DWORD dst_unused:UNUSED_PAD src0_sel:WORD_1
	v_cvt_f32_f16_e32 v16, v80
	v_cvt_f32_f16_sdwa v19, v81 dst_sel:DWORD dst_unused:UNUSED_PAD src0_sel:WORD_1
	v_cvt_f32_f16_e32 v18, v81
	v_pk_mul_f32 v[22:23], v[0:1], v[30:31]
	v_pk_mul_f32 v[20:21], v[2:3], v[92:93]
	v_pk_mul_f32 v[96:97], v[22:23], v[22:23]
	ds_read_b128 v[12:15], v94 offset:7936
	v_pk_mul_f32 v[94:95], v[20:21], v[20:21]
	v_add_f32_e32 v42, v96, v97
	v_cvt_f32_f16_sdwa v25, v70 dst_sel:DWORD dst_unused:UNUSED_PAD src0_sel:WORD_1
	v_cvt_f32_f16_e32 v24, v70
	v_cvt_f32_f16_sdwa v27, v71 dst_sel:DWORD dst_unused:UNUSED_PAD src0_sel:WORD_1
	v_cvt_f32_f16_e32 v26, v71
	v_add_f32_e32 v42, v94, v42
	v_add_f32_e32 v42, v95, v42
	v_pk_add_f32 v[94:95], v[16:17], -1.0 op_sel_hi:[1,0]
	v_pk_add_f32 v[96:97], v[18:19], -1.0 op_sel_hi:[1,0]
	v_pk_fma_f32 v[94:95], v[4:5], v[94:95], 1.0 op_sel_hi:[1,1,0]
	v_pk_fma_f32 v[96:97], v[6:7], v[96:97], 1.0 op_sel_hi:[1,1,0]
	v_pk_mul_f32 v[94:95], v[30:31], v[94:95]
	v_pk_mul_f32 v[96:97], v[92:93], v[96:97]
	v_pk_mul_f32 v[30:31], v[24:25], v[94:95]
	v_pk_mul_f32 v[92:93], v[26:27], v[96:97]
	v_pk_mul_f32 v[30:31], v[8:9], v[30:31]
	v_pk_mul_f32 v[92:93], v[10:11], v[92:93]
	v_add_f32_e32 v30, v30, v31
	v_add_f32_e32 v31, v92, v93
	v_add_f32_e32 v30, v30, v31
	v_add_f32_dpp v42, v42, v42 quad_perm:[1,0,3,2] row_mask:0xf bank_mask:0xf bound_ctrl:1
	s_nop 0
	v_add_f32_dpp v30, v30, v30 quad_perm:[1,0,3,2] row_mask:0xf bank_mask:0xf bound_ctrl:1
	v_add_f32_dpp v42, v42, v42 quad_perm:[2,3,0,1] row_mask:0xf bank_mask:0xf bound_ctrl:1
	s_nop 0
	v_add_f32_dpp v30, v30, v30 quad_perm:[2,3,0,1] row_mask:0xf bank_mask:0xf bound_ctrl:1
	v_add_f32_dpp v42, v42, v42 row_half_mirror row_mask:0xf bank_mask:0xf bound_ctrl:1
	s_nop 0
	v_add_f32_dpp v30, v30, v30 row_half_mirror row_mask:0xf bank_mask:0xf bound_ctrl:1
	v_mov_b32_dpp v116, v42 row_mirror row_mask:0xf bank_mask:0xf bound_ctrl:1
	s_nop 0
	v_mov_b32_dpp v31, v30 row_mirror row_mask:0xf bank_mask:0xf bound_ctrl:1
	s_and_saveexec_b64 s[12:13], s[6:7]
	s_cbranch_execz .LBB0_430
	s_add_i32 s42, s95, 16
	v_cmp_lt_u32_e32 vcc, s42, v106
	s_and_b64 exec, exec, vcc
	s_cbranch_execz .LBB0_430
	v_add_f32_e32 v92, v30, v31
	v_add_u32_e32 v30, s42, v46
	v_ashrrev_i32_e32 v31, 31, v30
	v_lshlrev_b64 v[30:31], 6, v[30:31]
	v_lshl_add_u64 v[30:31], s[58:59], 0, v[30:31]
	global_store_dword v[30:31], v92, off

.LBB0_437:
	v_swap_b32 v93, v94
	v_swap_b32 v33, v34
	s_waitcnt lgkmcnt(0)
	v_pk_mul_f32 v[130:131], v[92:93], v[24:25] op_sel_hi:[1,0]
	v_pk_fma_f32 v[130:131], v[94:95], v[24:25], v[130:131] op_sel:[0,1,0]
	v_pk_fma_f32 v[130:131], v[32:33], v[26:27], v[130:131] op_sel_hi:[1,0,1]
	v_pk_fma_f32 v[130:131], v[34:35], v[26:27], v[130:131] op_sel:[0,1,0]
	v_pk_fma_f32 v[92:93], v[28:29], v[96:97], v[92:93] op_sel_hi:[0,1,1]
	v_pk_fma_f32 v[94:95], v[28:29], v[96:97], v[94:95] op_sel:[1,0,0]
	v_add_f32_dpp v130, v130, v130 quad_perm:[1,0,3,2] row_mask:0xf bank_mask:0xf bound_ctrl:1
	v_add_f32_dpp v131, v131, v131 quad_perm:[1,0,3,2] row_mask:0xf bank_mask:0xf bound_ctrl:1
	v_pk_fma_f32 v[32:33], v[30:31], v[96:97], v[32:33] op_sel_hi:[0,1,1]
	v_add_f32_dpp v130, v130, v130 quad_perm:[2,3,0,1] row_mask:0xf bank_mask:0xf bound_ctrl:1
	v_add_f32_dpp v131, v131, v131 quad_perm:[2,3,0,1] row_mask:0xf bank_mask:0xf bound_ctrl:1
	v_pk_fma_f32 v[34:35], v[30:31], v[96:97], v[34:35] op_sel:[1,0,0]
	v_add_f32_dpp v130, v130, v130 row_half_mirror row_mask:0xf bank_mask:0xf bound_ctrl:1
	v_add_f32_dpp v131, v131, v131 row_half_mirror row_mask:0xf bank_mask:0xf bound_ctrl:1
	ds_read_b128 v[12:15], v113 offset:12288
	ds_read_b128 v[116:119], v113 offset:16384
	ds_read_b128 v[120:123], v113 offset:8192
	ds_read_b128 v[124:127], v113
	ds_read_b64 v[90:91], v112
	v_add_f32_dpp v130, v130, v130 row_mirror row_mask:0xf bank_mask:0xf bound_ctrl:1
	v_add_f32_dpp v131, v131, v131 row_mirror row_mask:0xf bank_mask:0xf bound_ctrl:1
	v_pk_fma_f32 v[92:93], v[20:21], v[130:131], v[92:93] op_sel_hi:[0,1,1]
	v_pk_fma_f32 v[94:95], v[20:21], v[130:131], v[94:95] op_sel:[1,0,0]
	v_pk_fma_f32 v[32:33], v[22:23], v[130:131], v[32:33] op_sel_hi:[0,1,1]
	v_pk_fma_f32 v[34:35], v[22:23], v[130:131], v[34:35] op_sel:[1,0,0]
	s_waitcnt lgkmcnt(4)
	v_pk_mul_f32 v[130:131], v[92:93], v[12:13] op_sel_hi:[1,0]
	v_pk_mul_f32 v[20:21], v[92:93], v[16:17] op_sel_hi:[1,0]
	v_pk_fma_f32 v[130:131], v[94:95], v[12:13], v[130:131] op_sel:[0,1,0]
	v_pk_fma_f32 v[20:21], v[94:95], v[16:17], v[20:21] op_sel:[0,1,0]
	v_pk_fma_f32 v[130:131], v[32:33], v[14:15], v[130:131] op_sel_hi:[1,0,1]
	v_pk_fma_f32 v[20:21], v[32:33], v[18:19], v[20:21] op_sel_hi:[1,0,1]
	v_pk_fma_f32 v[130:131], v[34:35], v[14:15], v[130:131] op_sel:[0,1,0]
	v_pk_fma_f32 v[20:21], v[34:35], v[18:19], v[20:21] op_sel:[0,1,0]
	v_cvt_pk_f16_f32 v20, v20, v21
	v_add_f32_dpp v130, v130, v130 quad_perm:[1,0,3,2] row_mask:0xf bank_mask:0xf bound_ctrl:1
	v_add_f32_dpp v131, v131, v131 quad_perm:[1,0,3,2] row_mask:0xf bank_mask:0xf bound_ctrl:1
	ds_write_b32 v47, v20
	ds_read_b128 v[24:27], v114 offset:12800
	ds_read_b128 v[20:23], v114 offset:16896
	ds_read_b128 v[28:31], v114 offset:8704
	ds_read_b128 v[16:19], v114 offset:512
	s_waitcnt lgkmcnt(5)
	v_pk_fma_f32 v[92:93], v[120:121], v[90:91], v[92:93] op_sel_hi:[0,1,1]
	v_add_f32_dpp v130, v130, v130 quad_perm:[2,3,0,1] row_mask:0xf bank_mask:0xf bound_ctrl:1
	v_add_f32_dpp v131, v131, v131 quad_perm:[2,3,0,1] row_mask:0xf bank_mask:0xf bound_ctrl:1
	v_pk_fma_f32 v[94:95], v[120:121], v[90:91], v[94:95] op_sel:[1,0,0]
	v_add_f32_dpp v130, v130, v130 row_half_mirror row_mask:0xf bank_mask:0xf bound_ctrl:1
	v_add_f32_dpp v131, v131, v131 row_half_mirror row_mask:0xf bank_mask:0xf bound_ctrl:1
	v_pk_fma_f32 v[32:33], v[122:123], v[90:91], v[32:33] op_sel_hi:[0,1,1]
	v_pk_fma_f32 v[34:35], v[122:123], v[90:91], v[34:35] op_sel:[1,0,0]
	v_add_f32_dpp v130, v130, v130 row_mirror row_mask:0xf bank_mask:0xf bound_ctrl:1
	v_add_f32_dpp v131, v131, v131 row_mirror row_mask:0xf bank_mask:0xf bound_ctrl:1
	v_pk_fma_f32 v[92:93], v[116:117], v[130:131], v[92:93] op_sel_hi:[0,1,1]
	v_pk_fma_f32 v[94:95], v[116:117], v[130:131], v[94:95] op_sel:[1,0,0]
	v_pk_fma_f32 v[32:33], v[118:119], v[130:131], v[32:33] op_sel_hi:[0,1,1]
	v_pk_fma_f32 v[34:35], v[118:119], v[130:131], v[34:35] op_sel:[1,0,0]
	ds_read_b64 v[96:97], v115 offset:20736
	v_pk_mul_f32 v[12:13], v[92:93], v[124:125] op_sel_hi:[1,0]
	v_pk_fma_f32 v[12:13], v[94:95], v[124:125], v[12:13] op_sel:[0,1,0]
	v_pk_fma_f32 v[12:13], v[32:33], v[126:127], v[12:13] op_sel_hi:[1,0,1]
	v_pk_fma_f32 v[12:13], v[34:35], v[126:127], v[12:13] op_sel:[0,1,0]
	v_cvt_pk_f16_f32 v12, v12, v13
	ds_write_b32 v47, v12 offset:1024
	s_waitcnt lgkmcnt(0)
	v_pk_mul_f32 v[130:131], v[92:93], v[24:25] op_sel_hi:[1,0]
	v_pk_fma_f32 v[130:131], v[94:95], v[24:25], v[130:131] op_sel:[0,1,0]
	v_pk_fma_f32 v[130:131], v[32:33], v[26:27], v[130:131] op_sel_hi:[1,0,1]
	v_pk_fma_f32 v[130:131], v[34:35], v[26:27], v[130:131] op_sel:[0,1,0]
	v_pk_fma_f32 v[92:93], v[28:29], v[96:97], v[92:93] op_sel_hi:[0,1,1]
	v_pk_fma_f32 v[94:95], v[28:29], v[96:97], v[94:95] op_sel:[1,0,0]
	v_add_f32_dpp v130, v130, v130 quad_perm:[1,0,3,2] row_mask:0xf bank_mask:0xf bound_ctrl:1
	v_add_f32_dpp v131, v131, v131 quad_perm:[1,0,3,2] row_mask:0xf bank_mask:0xf bound_ctrl:1
	v_pk_fma_f32 v[32:33], v[30:31], v[96:97], v[32:33] op_sel_hi:[0,1,1]
	v_add_f32_dpp v130, v130, v130 quad_perm:[2,3,0,1] row_mask:0xf bank_mask:0xf bound_ctrl:1
	v_add_f32_dpp v131, v131, v131 quad_perm:[2,3,0,1] row_mask:0xf bank_mask:0xf bound_ctrl:1
	v_pk_fma_f32 v[34:35], v[30:31], v[96:97], v[34:35] op_sel:[1,0,0]
	v_add_f32_dpp v130, v130, v130 row_half_mirror row_mask:0xf bank_mask:0xf bound_ctrl:1
	v_add_f32_dpp v131, v131, v131 row_half_mirror row_mask:0xf bank_mask:0xf bound_ctrl:1
	ds_read_b128 v[12:15], v113 offset:12800
	ds_read_b128 v[116:119], v113 offset:16896
	ds_read_b128 v[120:123], v113 offset:8704
	ds_read_b128 v[124:127], v113 offset:512
	ds_read_b64 v[90:91], v112 offset:256
	v_add_f32_dpp v130, v130, v130 row_mirror row_mask:0xf bank_mask:0xf bound_ctrl:1
	v_add_f32_dpp v131, v131, v131 row_mirror row_mask:0xf bank_mask:0xf bound_ctrl:1
	v_pk_fma_f32 v[92:93], v[20:21], v[130:131], v[92:93] op_sel_hi:[0,1,1]
	v_pk_fma_f32 v[94:95], v[20:21], v[130:131], v[94:95] op_sel:[1,0,0]
	v_pk_fma_f32 v[32:33], v[22:23], v[130:131], v[32:33] op_sel_hi:[0,1,1]
	v_pk_fma_f32 v[34:35], v[22:23], v[130:131], v[34:35] op_sel:[1,0,0]
	s_waitcnt lgkmcnt(4)
	v_pk_mul_f32 v[130:131], v[92:93], v[12:13] op_sel_hi:[1,0]
	v_pk_mul_f32 v[20:21], v[92:93], v[16:17] op_sel_hi:[1,0]
	v_pk_fma_f32 v[130:131], v[94:95], v[12:13], v[130:131] op_sel:[0,1,0]
	v_pk_fma_f32 v[20:21], v[94:95], v[16:17], v[20:21] op_sel:[0,1,0]
	v_pk_fma_f32 v[130:131], v[32:33], v[14:15], v[130:131] op_sel_hi:[1,0,1]
	v_pk_fma_f32 v[20:21], v[32:33], v[18:19], v[20:21] op_sel_hi:[1,0,1]
	v_pk_fma_f32 v[130:131], v[34:35], v[14:15], v[130:131] op_sel:[0,1,0]
	v_pk_fma_f32 v[20:21], v[34:35], v[18:19], v[20:21] op_sel:[0,1,0]
	v_cvt_pk_f16_f32 v20, v20, v21
	v_add_f32_dpp v130, v130, v130 quad_perm:[1,0,3,2] row_mask:0xf bank_mask:0xf bound_ctrl:1
	v_add_f32_dpp v131, v131, v131 quad_perm:[1,0,3,2] row_mask:0xf bank_mask:0xf bound_ctrl:1
	ds_write_b32 v47, v20 offset:2048
	ds_read_b128 v[24:27], v114 offset:13312
	ds_read_b128 v[20:23], v114 offset:17408
	ds_read_b128 v[28:31], v114 offset:9216
	ds_read_b128 v[16:19], v114 offset:1024
	s_waitcnt lgkmcnt(5)
	v_pk_fma_f32 v[92:93], v[120:121], v[90:91], v[92:93] op_sel_hi:[0,1,1]
	v_add_f32_dpp v130, v130, v130 quad_perm:[2,3,0,1] row_mask:0xf bank_mask:0xf bound_ctrl:1
	v_add_f32_dpp v131, v131, v131 quad_perm:[2,3,0,1] row_mask:0xf bank_mask:0xf bound_ctrl:1
	v_pk_fma_f32 v[94:95], v[120:121], v[90:91], v[94:95] op_sel:[1,0,0]
	v_add_f32_dpp v130, v130, v130 row_half_mirror row_mask:0xf bank_mask:0xf bound_ctrl:1
	v_add_f32_dpp v131, v131, v131 row_half_mirror row_mask:0xf bank_mask:0xf bound_ctrl:1
	v_pk_fma_f32 v[32:33], v[122:123], v[90:91], v[32:33] op_sel_hi:[0,1,1]
	v_pk_fma_f32 v[34:35], v[122:123], v[90:91], v[34:35] op_sel:[1,0,0]
	v_add_f32_dpp v130, v130, v130 row_mirror row_mask:0xf bank_mask:0xf bound_ctrl:1
	v_add_f32_dpp v131, v131, v131 row_mirror row_mask:0xf bank_mask:0xf bound_ctrl:1
	v_pk_fma_f32 v[92:93], v[116:117], v[130:131], v[92:93] op_sel_hi:[0,1,1]
	v_pk_fma_f32 v[94:95], v[116:117], v[130:131], v[94:95] op_sel:[1,0,0]
	v_pk_fma_f32 v[32:33], v[118:119], v[130:131], v[32:33] op_sel_hi:[0,1,1]
	v_pk_fma_f32 v[34:35], v[118:119], v[130:131], v[34:35] op_sel:[1,0,0]
	ds_read_b64 v[96:97], v115 offset:20992
	v_pk_mul_f32 v[12:13], v[92:93], v[124:125] op_sel_hi:[1,0]
	v_pk_fma_f32 v[12:13], v[94:95], v[124:125], v[12:13] op_sel:[0,1,0]
	v_pk_fma_f32 v[12:13], v[32:33], v[126:127], v[12:13] op_sel_hi:[1,0,1]
	v_pk_fma_f32 v[12:13], v[34:35], v[126:127], v[12:13] op_sel:[0,1,0]
	v_cvt_pk_f16_f32 v12, v12, v13
	ds_write_b32 v47, v12 offset:3072
	s_waitcnt lgkmcnt(0)
	v_pk_mul_f32 v[130:131], v[92:93], v[24:25] op_sel_hi:[1,0]
	v_pk_fma_f32 v[130:131], v[94:95], v[24:25], v[130:131] op_sel:[0,1,0]
	v_pk_fma_f32 v[130:131], v[32:33], v[26:27], v[130:131] op_sel_hi:[1,0,1]
	v_pk_fma_f32 v[130:131], v[34:35], v[26:27], v[130:131] op_sel:[0,1,0]
	v_pk_fma_f32 v[92:93], v[28:29], v[96:97], v[92:93] op_sel_hi:[0,1,1]
	v_pk_fma_f32 v[94:95], v[28:29], v[96:97], v[94:95] op_sel:[1,0,0]
	v_add_f32_dpp v130, v130, v130 quad_perm:[1,0,3,2] row_mask:0xf bank_mask:0xf bound_ctrl:1
	v_add_f32_dpp v131, v131, v131 quad_perm:[1,0,3,2] row_mask:0xf bank_mask:0xf bound_ctrl:1
	v_pk_fma_f32 v[32:33], v[30:31], v[96:97], v[32:33] op_sel_hi:[0,1,1]
	v_add_f32_dpp v130, v130, v130 quad_perm:[2,3,0,1] row_mask:0xf bank_mask:0xf bound_ctrl:1
	v_add_f32_dpp v131, v131, v131 quad_perm:[2,3,0,1] row_mask:0xf bank_mask:0xf bound_ctrl:1
	v_pk_fma_f32 v[34:35], v[30:31], v[96:97], v[34:35] op_sel:[1,0,0]
	v_add_f32_dpp v130, v130, v130 row_half_mirror row_mask:0xf bank_mask:0xf bound_ctrl:1
	v_add_f32_dpp v131, v131, v131 row_half_mirror row_mask:0xf bank_mask:0xf bound_ctrl:1
	ds_read_b128 v[12:15], v113 offset:13312
	ds_read_b128 v[116:119], v113 offset:17408
	ds_read_b128 v[120:123], v113 offset:9216
	ds_read_b128 v[124:127], v113 offset:1024
	ds_read_b64 v[90:91], v112 offset:512
	v_add_f32_dpp v130, v130, v130 row_mirror row_mask:0xf bank_mask:0xf bound_ctrl:1
	v_add_f32_dpp v131, v131, v131 row_mirror row_mask:0xf bank_mask:0xf bound_ctrl:1
	v_pk_fma_f32 v[92:93], v[20:21], v[130:131], v[92:93] op_sel_hi:[0,1,1]
	v_pk_fma_f32 v[94:95], v[20:21], v[130:131], v[94:95] op_sel:[1,0,0]
	v_pk_fma_f32 v[32:33], v[22:23], v[130:131], v[32:33] op_sel_hi:[0,1,1]
	v_pk_fma_f32 v[34:35], v[22:23], v[130:131], v[34:35] op_sel:[1,0,0]
	s_waitcnt lgkmcnt(4)
	v_pk_mul_f32 v[130:131], v[92:93], v[12:13] op_sel_hi:[1,0]
	v_pk_mul_f32 v[20:21], v[92:93], v[16:17] op_sel_hi:[1,0]
	v_pk_fma_f32 v[130:131], v[94:95], v[12:13], v[130:131] op_sel:[0,1,0]
	v_pk_fma_f32 v[20:21], v[94:95], v[16:17], v[20:21] op_sel:[0,1,0]
	v_pk_fma_f32 v[130:131], v[32:33], v[14:15], v[130:131] op_sel_hi:[1,0,1]
	v_pk_fma_f32 v[20:21], v[32:33], v[18:19], v[20:21] op_sel_hi:[1,0,1]
	v_pk_fma_f32 v[130:131], v[34:35], v[14:15], v[130:131] op_sel:[0,1,0]
	v_pk_fma_f32 v[20:21], v[34:35], v[18:19], v[20:21] op_sel:[0,1,0]
	v_cvt_pk_f16_f32 v20, v20, v21
	v_add_f32_dpp v130, v130, v130 quad_perm:[1,0,3,2] row_mask:0xf bank_mask:0xf bound_ctrl:1
	v_add_f32_dpp v131, v131, v131 quad_perm:[1,0,3,2] row_mask:0xf bank_mask:0xf bound_ctrl:1
	ds_write_b32 v47, v20 offset:4096
	ds_read_b128 v[24:27], v114 offset:13824
	ds_read_b128 v[20:23], v114 offset:17920
	ds_read_b128 v[28:31], v114 offset:9728
	ds_read_b128 v[16:19], v114 offset:1536
	s_waitcnt lgkmcnt(5)
	v_pk_fma_f32 v[92:93], v[120:121], v[90:91], v[92:93] op_sel_hi:[0,1,1]
	v_add_f32_dpp v130, v130, v130 quad_perm:[2,3,0,1] row_mask:0xf bank_mask:0xf bound_ctrl:1
	v_add_f32_dpp v131, v131, v131 quad_perm:[2,3,0,1] row_mask:0xf bank_mask:0xf bound_ctrl:1
	v_pk_fma_f32 v[94:95], v[120:121], v[90:91], v[94:95] op_sel:[1,0,0]
	v_add_f32_dpp v130, v130, v130 row_half_mirror row_mask:0xf bank_mask:0xf bound_ctrl:1
	v_add_f32_dpp v131, v131, v131 row_half_mirror row_mask:0xf bank_mask:0xf bound_ctrl:1
	v_pk_fma_f32 v[32:33], v[122:123], v[90:91], v[32:33] op_sel_hi:[0,1,1]
	v_pk_fma_f32 v[34:35], v[122:123], v[90:91], v[34:35] op_sel:[1,0,0]
	v_add_f32_dpp v130, v130, v130 row_mirror row_mask:0xf bank_mask:0xf bound_ctrl:1
	v_add_f32_dpp v131, v131, v131 row_mirror row_mask:0xf bank_mask:0xf bound_ctrl:1
	v_pk_fma_f32 v[92:93], v[116:117], v[130:131], v[92:93] op_sel_hi:[0,1,1]
	v_pk_fma_f32 v[94:95], v[116:117], v[130:131], v[94:95] op_sel:[1,0,0]
	v_pk_fma_f32 v[32:33], v[118:119], v[130:131], v[32:33] op_sel_hi:[0,1,1]
	v_pk_fma_f32 v[34:35], v[118:119], v[130:131], v[34:35] op_sel:[1,0,0]
	ds_read_b64 v[96:97], v115 offset:21248
	v_pk_mul_f32 v[12:13], v[92:93], v[124:125] op_sel_hi:[1,0]
	v_pk_fma_f32 v[12:13], v[94:95], v[124:125], v[12:13] op_sel:[0,1,0]
	v_pk_fma_f32 v[12:13], v[32:33], v[126:127], v[12:13] op_sel_hi:[1,0,1]
	v_pk_fma_f32 v[12:13], v[34:35], v[126:127], v[12:13] op_sel:[0,1,0]
	v_cvt_pk_f16_f32 v12, v12, v13
	ds_write_b32 v47, v12 offset:5120
	s_waitcnt lgkmcnt(0)
	v_pk_mul_f32 v[130:131], v[92:93], v[24:25] op_sel_hi:[1,0]
	v_pk_fma_f32 v[130:131], v[94:95], v[24:25], v[130:131] op_sel:[0,1,0]
	v_pk_fma_f32 v[130:131], v[32:33], v[26:27], v[130:131] op_sel_hi:[1,0,1]
	v_pk_fma_f32 v[130:131], v[34:35], v[26:27], v[130:131] op_sel:[0,1,0]
	v_pk_fma_f32 v[92:93], v[28:29], v[96:97], v[92:93] op_sel_hi:[0,1,1]
	v_pk_fma_f32 v[94:95], v[28:29], v[96:97], v[94:95] op_sel:[1,0,0]
	v_add_f32_dpp v130, v130, v130 quad_perm:[1,0,3,2] row_mask:0xf bank_mask:0xf bound_ctrl:1
	v_add_f32_dpp v131, v131, v131 quad_perm:[1,0,3,2] row_mask:0xf bank_mask:0xf bound_ctrl:1
	v_pk_fma_f32 v[32:33], v[30:31], v[96:97], v[32:33] op_sel_hi:[0,1,1]
	v_add_f32_dpp v130, v130, v130 quad_perm:[2,3,0,1] row_mask:0xf bank_mask:0xf bound_ctrl:1
	v_add_f32_dpp v131, v131, v131 quad_perm:[2,3,0,1] row_mask:0xf bank_mask:0xf bound_ctrl:1
	v_pk_fma_f32 v[34:35], v[30:31], v[96:97], v[34:35] op_sel:[1,0,0]
	v_add_f32_dpp v130, v130, v130 row_half_mirror row_mask:0xf bank_mask:0xf bound_ctrl:1
	v_add_f32_dpp v131, v131, v131 row_half_mirror row_mask:0xf bank_mask:0xf bound_ctrl:1
	ds_read_b128 v[12:15], v113 offset:13824
	ds_read_b128 v[116:119], v113 offset:17920
	ds_read_b128 v[120:123], v113 offset:9728
	ds_read_b128 v[124:127], v113 offset:1536
	ds_read_b64 v[90:91], v112 offset:768
	v_add_f32_dpp v130, v130, v130 row_mirror row_mask:0xf bank_mask:0xf bound_ctrl:1
	v_add_f32_dpp v131, v131, v131 row_mirror row_mask:0xf bank_mask:0xf bound_ctrl:1
	v_pk_fma_f32 v[92:93], v[20:21], v[130:131], v[92:93] op_sel_hi:[0,1,1]
	v_pk_fma_f32 v[94:95], v[20:21], v[130:131], v[94:95] op_sel:[1,0,0]
	v_pk_fma_f32 v[32:33], v[22:23], v[130:131], v[32:33] op_sel_hi:[0,1,1]
	v_pk_fma_f32 v[34:35], v[22:23], v[130:131], v[34:35] op_sel:[1,0,0]
	s_waitcnt lgkmcnt(4)
	v_pk_mul_f32 v[130:131], v[92:93], v[12:13] op_sel_hi:[1,0]
	v_pk_mul_f32 v[20:21], v[92:93], v[16:17] op_sel_hi:[1,0]
	v_pk_fma_f32 v[130:131], v[94:95], v[12:13], v[130:131] op_sel:[0,1,0]
	v_pk_fma_f32 v[20:21], v[94:95], v[16:17], v[20:21] op_sel:[0,1,0]
	v_pk_fma_f32 v[130:131], v[32:33], v[14:15], v[130:131] op_sel_hi:[1,0,1]
	v_pk_fma_f32 v[20:21], v[32:33], v[18:19], v[20:21] op_sel_hi:[1,0,1]
	v_pk_fma_f32 v[130:131], v[34:35], v[14:15], v[130:131] op_sel:[0,1,0]
	v_pk_fma_f32 v[20:21], v[34:35], v[18:19], v[20:21] op_sel:[0,1,0]
	v_cvt_pk_f16_f32 v20, v20, v21
	v_add_f32_dpp v130, v130, v130 quad_perm:[1,0,3,2] row_mask:0xf bank_mask:0xf bound_ctrl:1
	v_add_f32_dpp v131, v131, v131 quad_perm:[1,0,3,2] row_mask:0xf bank_mask:0xf bound_ctrl:1
	ds_write_b32 v47, v20 offset:6144
	ds_read_b128 v[24:27], v114 offset:14336
	ds_read_b128 v[20:23], v114 offset:18432
	ds_read_b128 v[28:31], v114 offset:10240
	ds_read_b128 v[16:19], v114 offset:2048
	s_waitcnt lgkmcnt(5)
	v_pk_fma_f32 v[92:93], v[120:121], v[90:91], v[92:93] op_sel_hi:[0,1,1]
	v_add_f32_dpp v130, v130, v130 quad_perm:[2,3,0,1] row_mask:0xf bank_mask:0xf bound_ctrl:1
	v_add_f32_dpp v131, v131, v131 quad_perm:[2,3,0,1] row_mask:0xf bank_mask:0xf bound_ctrl:1
	v_pk_fma_f32 v[94:95], v[120:121], v[90:91], v[94:95] op_sel:[1,0,0]
	v_add_f32_dpp v130, v130, v130 row_half_mirror row_mask:0xf bank_mask:0xf bound_ctrl:1
	v_add_f32_dpp v131, v131, v131 row_half_mirror row_mask:0xf bank_mask:0xf bound_ctrl:1
	v_pk_fma_f32 v[32:33], v[122:123], v[90:91], v[32:33] op_sel_hi:[0,1,1]
	v_pk_fma_f32 v[34:35], v[122:123], v[90:91], v[34:35] op_sel:[1,0,0]
	v_add_f32_dpp v130, v130, v130 row_mirror row_mask:0xf bank_mask:0xf bound_ctrl:1
	v_add_f32_dpp v131, v131, v131 row_mirror row_mask:0xf bank_mask:0xf bound_ctrl:1
	v_pk_fma_f32 v[92:93], v[116:117], v[130:131], v[92:93] op_sel_hi:[0,1,1]
	v_pk_fma_f32 v[94:95], v[116:117], v[130:131], v[94:95] op_sel:[1,0,0]
	v_pk_fma_f32 v[32:33], v[118:119], v[130:131], v[32:33] op_sel_hi:[0,1,1]
	v_pk_fma_f32 v[34:35], v[118:119], v[130:131], v[34:35] op_sel:[1,0,0]
	ds_read_b64 v[96:97], v115 offset:21504
	v_pk_mul_f32 v[12:13], v[92:93], v[124:125] op_sel_hi:[1,0]
	v_pk_fma_f32 v[12:13], v[94:95], v[124:125], v[12:13] op_sel:[0,1,0]
	v_pk_fma_f32 v[12:13], v[32:33], v[126:127], v[12:13] op_sel_hi:[1,0,1]
	v_pk_fma_f32 v[12:13], v[34:35], v[126:127], v[12:13] op_sel:[0,1,0]
	v_cvt_pk_f16_f32 v12, v12, v13
	ds_write_b32 v47, v12 offset:7168
	s_waitcnt lgkmcnt(0)
	v_pk_mul_f32 v[130:131], v[92:93], v[24:25] op_sel_hi:[1,0]
	v_pk_fma_f32 v[130:131], v[94:95], v[24:25], v[130:131] op_sel:[0,1,0]
	v_pk_fma_f32 v[130:131], v[32:33], v[26:27], v[130:131] op_sel_hi:[1,0,1]
	v_pk_fma_f32 v[130:131], v[34:35], v[26:27], v[130:131] op_sel:[0,1,0]
	v_pk_fma_f32 v[92:93], v[28:29], v[96:97], v[92:93] op_sel_hi:[0,1,1]
	v_pk_fma_f32 v[94:95], v[28:29], v[96:97], v[94:95] op_sel:[1,0,0]
	v_add_f32_dpp v130, v130, v130 quad_perm:[1,0,3,2] row_mask:0xf bank_mask:0xf bound_ctrl:1
	v_add_f32_dpp v131, v131, v131 quad_perm:[1,0,3,2] row_mask:0xf bank_mask:0xf bound_ctrl:1
	v_pk_fma_f32 v[32:33], v[30:31], v[96:97], v[32:33] op_sel_hi:[0,1,1]
	v_add_f32_dpp v130, v130, v130 quad_perm:[2,3,0,1] row_mask:0xf bank_mask:0xf bound_ctrl:1
	v_add_f32_dpp v131, v131, v131 quad_perm:[2,3,0,1] row_mask:0xf bank_mask:0xf bound_ctrl:1
	v_pk_fma_f32 v[34:35], v[30:31], v[96:97], v[34:35] op_sel:[1,0,0]
	v_add_f32_dpp v130, v130, v130 row_half_mirror row_mask:0xf bank_mask:0xf bound_ctrl:1
	v_add_f32_dpp v131, v131, v131 row_half_mirror row_mask:0xf bank_mask:0xf bound_ctrl:1
	ds_read_b128 v[12:15], v113 offset:14336
	ds_read_b128 v[116:119], v113 offset:18432
	ds_read_b128 v[120:123], v113 offset:10240
	ds_read_b128 v[124:127], v113 offset:2048
	ds_read_b64 v[90:91], v112 offset:1024
	v_add_f32_dpp v130, v130, v130 row_mirror row_mask:0xf bank_mask:0xf bound_ctrl:1
	v_add_f32_dpp v131, v131, v131 row_mirror row_mask:0xf bank_mask:0xf bound_ctrl:1
	v_pk_fma_f32 v[92:93], v[20:21], v[130:131], v[92:93] op_sel_hi:[0,1,1]
	v_pk_fma_f32 v[94:95], v[20:21], v[130:131], v[94:95] op_sel:[1,0,0]
	v_pk_fma_f32 v[32:33], v[22:23], v[130:131], v[32:33] op_sel_hi:[0,1,1]
	v_pk_fma_f32 v[34:35], v[22:23], v[130:131], v[34:35] op_sel:[1,0,0]
	s_waitcnt lgkmcnt(4)
	v_pk_mul_f32 v[130:131], v[92:93], v[12:13] op_sel_hi:[1,0]
	v_pk_mul_f32 v[20:21], v[92:93], v[16:17] op_sel_hi:[1,0]
	v_pk_fma_f32 v[130:131], v[94:95], v[12:13], v[130:131] op_sel:[0,1,0]
	v_pk_fma_f32 v[20:21], v[94:95], v[16:17], v[20:21] op_sel:[0,1,0]
	v_pk_fma_f32 v[130:131], v[32:33], v[14:15], v[130:131] op_sel_hi:[1,0,1]
	v_pk_fma_f32 v[20:21], v[32:33], v[18:19], v[20:21] op_sel_hi:[1,0,1]
	v_pk_fma_f32 v[130:131], v[34:35], v[14:15], v[130:131] op_sel:[0,1,0]
	v_pk_fma_f32 v[20:21], v[34:35], v[18:19], v[20:21] op_sel:[0,1,0]
	v_cvt_pk_f16_f32 v20, v20, v21
	v_add_f32_dpp v130, v130, v130 quad_perm:[1,0,3,2] row_mask:0xf bank_mask:0xf bound_ctrl:1
	v_add_f32_dpp v131, v131, v131 quad_perm:[1,0,3,2] row_mask:0xf bank_mask:0xf bound_ctrl:1
	ds_write_b32 v47, v20 offset:8192
	ds_read_b128 v[24:27], v114 offset:14848
	ds_read_b128 v[20:23], v114 offset:18944
	ds_read_b128 v[28:31], v114 offset:10752
	ds_read_b128 v[16:19], v114 offset:2560
	s_waitcnt lgkmcnt(5)
	v_pk_fma_f32 v[92:93], v[120:121], v[90:91], v[92:93] op_sel_hi:[0,1,1]
	v_add_f32_dpp v130, v130, v130 quad_perm:[2,3,0,1] row_mask:0xf bank_mask:0xf bound_ctrl:1
	v_add_f32_dpp v131, v131, v131 quad_perm:[2,3,0,1] row_mask:0xf bank_mask:0xf bound_ctrl:1
	v_pk_fma_f32 v[94:95], v[120:121], v[90:91], v[94:95] op_sel:[1,0,0]
	v_add_f32_dpp v130, v130, v130 row_half_mirror row_mask:0xf bank_mask:0xf bound_ctrl:1
	v_add_f32_dpp v131, v131, v131 row_half_mirror row_mask:0xf bank_mask:0xf bound_ctrl:1
	v_pk_fma_f32 v[32:33], v[122:123], v[90:91], v[32:33] op_sel_hi:[0,1,1]
	v_pk_fma_f32 v[34:35], v[122:123], v[90:91], v[34:35] op_sel:[1,0,0]
	v_add_f32_dpp v130, v130, v130 row_mirror row_mask:0xf bank_mask:0xf bound_ctrl:1
	v_add_f32_dpp v131, v131, v131 row_mirror row_mask:0xf bank_mask:0xf bound_ctrl:1
	v_pk_fma_f32 v[92:93], v[116:117], v[130:131], v[92:93] op_sel_hi:[0,1,1]
	v_pk_fma_f32 v[94:95], v[116:117], v[130:131], v[94:95] op_sel:[1,0,0]
	v_pk_fma_f32 v[32:33], v[118:119], v[130:131], v[32:33] op_sel_hi:[0,1,1]
	v_pk_fma_f32 v[34:35], v[118:119], v[130:131], v[34:35] op_sel:[1,0,0]
	ds_read_b64 v[96:97], v115 offset:21760
	v_pk_mul_f32 v[12:13], v[92:93], v[124:125] op_sel_hi:[1,0]
	v_pk_fma_f32 v[12:13], v[94:95], v[124:125], v[12:13] op_sel:[0,1,0]
	v_pk_fma_f32 v[12:13], v[32:33], v[126:127], v[12:13] op_sel_hi:[1,0,1]
	v_pk_fma_f32 v[12:13], v[34:35], v[126:127], v[12:13] op_sel:[0,1,0]
	v_cvt_pk_f16_f32 v12, v12, v13
	ds_write_b32 v47, v12 offset:9216
	s_waitcnt lgkmcnt(0)
	v_pk_mul_f32 v[130:131], v[92:93], v[24:25] op_sel_hi:[1,0]
	v_pk_fma_f32 v[130:131], v[94:95], v[24:25], v[130:131] op_sel:[0,1,0]
	v_pk_fma_f32 v[130:131], v[32:33], v[26:27], v[130:131] op_sel_hi:[1,0,1]
	v_pk_fma_f32 v[130:131], v[34:35], v[26:27], v[130:131] op_sel:[0,1,0]
	v_pk_fma_f32 v[92:93], v[28:29], v[96:97], v[92:93] op_sel_hi:[0,1,1]
	v_pk_fma_f32 v[94:95], v[28:29], v[96:97], v[94:95] op_sel:[1,0,0]
	v_add_f32_dpp v130, v130, v130 quad_perm:[1,0,3,2] row_mask:0xf bank_mask:0xf bound_ctrl:1
	v_add_f32_dpp v131, v131, v131 quad_perm:[1,0,3,2] row_mask:0xf bank_mask:0xf bound_ctrl:1
	v_pk_fma_f32 v[32:33], v[30:31], v[96:97], v[32:33] op_sel_hi:[0,1,1]
	v_add_f32_dpp v130, v130, v130 quad_perm:[2,3,0,1] row_mask:0xf bank_mask:0xf bound_ctrl:1
	v_add_f32_dpp v131, v131, v131 quad_perm:[2,3,0,1] row_mask:0xf bank_mask:0xf bound_ctrl:1
	v_pk_fma_f32 v[34:35], v[30:31], v[96:97], v[34:35] op_sel:[1,0,0]
	v_add_f32_dpp v130, v130, v130 row_half_mirror row_mask:0xf bank_mask:0xf bound_ctrl:1
	v_add_f32_dpp v131, v131, v131 row_half_mirror row_mask:0xf bank_mask:0xf bound_ctrl:1
	ds_read_b128 v[12:15], v113 offset:14848
	ds_read_b128 v[116:119], v113 offset:18944
	ds_read_b128 v[120:123], v113 offset:10752
	ds_read_b128 v[124:127], v113 offset:2560
	ds_read_b64 v[90:91], v112 offset:1280
	v_add_f32_dpp v130, v130, v130 row_mirror row_mask:0xf bank_mask:0xf bound_ctrl:1
	v_add_f32_dpp v131, v131, v131 row_mirror row_mask:0xf bank_mask:0xf bound_ctrl:1
	v_pk_fma_f32 v[92:93], v[20:21], v[130:131], v[92:93] op_sel_hi:[0,1,1]
	v_pk_fma_f32 v[94:95], v[20:21], v[130:131], v[94:95] op_sel:[1,0,0]
	v_pk_fma_f32 v[32:33], v[22:23], v[130:131], v[32:33] op_sel_hi:[0,1,1]
	v_pk_fma_f32 v[34:35], v[22:23], v[130:131], v[34:35] op_sel:[1,0,0]
	s_waitcnt lgkmcnt(4)
	v_pk_mul_f32 v[130:131], v[92:93], v[12:13] op_sel_hi:[1,0]
	v_pk_mul_f32 v[20:21], v[92:93], v[16:17] op_sel_hi:[1,0]
	v_pk_fma_f32 v[130:131], v[94:95], v[12:13], v[130:131] op_sel:[0,1,0]
	v_pk_fma_f32 v[20:21], v[94:95], v[16:17], v[20:21] op_sel:[0,1,0]
	v_pk_fma_f32 v[130:131], v[32:33], v[14:15], v[130:131] op_sel_hi:[1,0,1]
	v_pk_fma_f32 v[20:21], v[32:33], v[18:19], v[20:21] op_sel_hi:[1,0,1]
	v_pk_fma_f32 v[130:131], v[34:35], v[14:15], v[130:131] op_sel:[0,1,0]
	v_pk_fma_f32 v[20:21], v[34:35], v[18:19], v[20:21] op_sel:[0,1,0]
	v_cvt_pk_f16_f32 v20, v20, v21
	v_add_f32_dpp v130, v130, v130 quad_perm:[1,0,3,2] row_mask:0xf bank_mask:0xf bound_ctrl:1
	v_add_f32_dpp v131, v131, v131 quad_perm:[1,0,3,2] row_mask:0xf bank_mask:0xf bound_ctrl:1
	ds_write_b32 v47, v20 offset:10240
	ds_read_b128 v[24:27], v114 offset:15360
	ds_read_b128 v[20:23], v114 offset:19456
	ds_read_b128 v[28:31], v114 offset:11264
	ds_read_b128 v[16:19], v114 offset:3072
	s_waitcnt lgkmcnt(5)
	v_pk_fma_f32 v[92:93], v[120:121], v[90:91], v[92:93] op_sel_hi:[0,1,1]
	v_add_f32_dpp v130, v130, v130 quad_perm:[2,3,0,1] row_mask:0xf bank_mask:0xf bound_ctrl:1
	v_add_f32_dpp v131, v131, v131 quad_perm:[2,3,0,1] row_mask:0xf bank_mask:0xf bound_ctrl:1
	v_pk_fma_f32 v[94:95], v[120:121], v[90:91], v[94:95] op_sel:[1,0,0]
	v_add_f32_dpp v130, v130, v130 row_half_mirror row_mask:0xf bank_mask:0xf bound_ctrl:1
	v_add_f32_dpp v131, v131, v131 row_half_mirror row_mask:0xf bank_mask:0xf bound_ctrl:1
	v_pk_fma_f32 v[32:33], v[122:123], v[90:91], v[32:33] op_sel_hi:[0,1,1]
	v_pk_fma_f32 v[34:35], v[122:123], v[90:91], v[34:35] op_sel:[1,0,0]
	v_add_f32_dpp v130, v130, v130 row_mirror row_mask:0xf bank_mask:0xf bound_ctrl:1
	v_add_f32_dpp v131, v131, v131 row_mirror row_mask:0xf bank_mask:0xf bound_ctrl:1
	v_pk_fma_f32 v[92:93], v[116:117], v[130:131], v[92:93] op_sel_hi:[0,1,1]
	v_pk_fma_f32 v[94:95], v[116:117], v[130:131], v[94:95] op_sel:[1,0,0]
	v_pk_fma_f32 v[32:33], v[118:119], v[130:131], v[32:33] op_sel_hi:[0,1,1]
	v_pk_fma_f32 v[34:35], v[118:119], v[130:131], v[34:35] op_sel:[1,0,0]
	ds_read_b64 v[96:97], v115 offset:22016
	v_pk_mul_f32 v[12:13], v[92:93], v[124:125] op_sel_hi:[1,0]
	v_pk_fma_f32 v[12:13], v[94:95], v[124:125], v[12:13] op_sel:[0,1,0]
	v_pk_fma_f32 v[12:13], v[32:33], v[126:127], v[12:13] op_sel_hi:[1,0,1]
	v_pk_fma_f32 v[12:13], v[34:35], v[126:127], v[12:13] op_sel:[0,1,0]
	v_cvt_pk_f16_f32 v12, v12, v13
	ds_write_b32 v47, v12 offset:11264
	s_waitcnt lgkmcnt(0)
	v_pk_mul_f32 v[130:131], v[92:93], v[24:25] op_sel_hi:[1,0]
	v_pk_fma_f32 v[130:131], v[94:95], v[24:25], v[130:131] op_sel:[0,1,0]
	v_pk_fma_f32 v[130:131], v[32:33], v[26:27], v[130:131] op_sel_hi:[1,0,1]
	v_pk_fma_f32 v[130:131], v[34:35], v[26:27], v[130:131] op_sel:[0,1,0]
	v_pk_fma_f32 v[92:93], v[28:29], v[96:97], v[92:93] op_sel_hi:[0,1,1]
	v_pk_fma_f32 v[94:95], v[28:29], v[96:97], v[94:95] op_sel:[1,0,0]
	v_add_f32_dpp v130, v130, v130 quad_perm:[1,0,3,2] row_mask:0xf bank_mask:0xf bound_ctrl:1
	v_add_f32_dpp v131, v131, v131 quad_perm:[1,0,3,2] row_mask:0xf bank_mask:0xf bound_ctrl:1
	v_pk_fma_f32 v[32:33], v[30:31], v[96:97], v[32:33] op_sel_hi:[0,1,1]
	v_add_f32_dpp v130, v130, v130 quad_perm:[2,3,0,1] row_mask:0xf bank_mask:0xf bound_ctrl:1
	v_add_f32_dpp v131, v131, v131 quad_perm:[2,3,0,1] row_mask:0xf bank_mask:0xf bound_ctrl:1
	v_pk_fma_f32 v[34:35], v[30:31], v[96:97], v[34:35] op_sel:[1,0,0]
	v_add_f32_dpp v130, v130, v130 row_half_mirror row_mask:0xf bank_mask:0xf bound_ctrl:1
	v_add_f32_dpp v131, v131, v131 row_half_mirror row_mask:0xf bank_mask:0xf bound_ctrl:1
	ds_read_b128 v[12:15], v113 offset:15360
	ds_read_b128 v[116:119], v113 offset:19456
	ds_read_b128 v[120:123], v113 offset:11264
	ds_read_b128 v[124:127], v113 offset:3072
	ds_read_b64 v[90:91], v112 offset:1536
	v_add_f32_dpp v130, v130, v130 row_mirror row_mask:0xf bank_mask:0xf bound_ctrl:1
	v_add_f32_dpp v131, v131, v131 row_mirror row_mask:0xf bank_mask:0xf bound_ctrl:1
	v_pk_fma_f32 v[92:93], v[20:21], v[130:131], v[92:93] op_sel_hi:[0,1,1]
	v_pk_fma_f32 v[94:95], v[20:21], v[130:131], v[94:95] op_sel:[1,0,0]
	v_pk_fma_f32 v[32:33], v[22:23], v[130:131], v[32:33] op_sel_hi:[0,1,1]
	v_pk_fma_f32 v[34:35], v[22:23], v[130:131], v[34:35] op_sel:[1,0,0]
	s_waitcnt lgkmcnt(4)
	v_pk_mul_f32 v[130:131], v[92:93], v[12:13] op_sel_hi:[1,0]
	v_pk_mul_f32 v[20:21], v[92:93], v[16:17] op_sel_hi:[1,0]
	v_pk_fma_f32 v[130:131], v[94:95], v[12:13], v[130:131] op_sel:[0,1,0]
	v_pk_fma_f32 v[20:21], v[94:95], v[16:17], v[20:21] op_sel:[0,1,0]
	v_pk_fma_f32 v[130:131], v[32:33], v[14:15], v[130:131] op_sel_hi:[1,0,1]
	v_pk_fma_f32 v[20:21], v[32:33], v[18:19], v[20:21] op_sel_hi:[1,0,1]
	v_pk_fma_f32 v[130:131], v[34:35], v[14:15], v[130:131] op_sel:[0,1,0]
	v_pk_fma_f32 v[20:21], v[34:35], v[18:19], v[20:21] op_sel:[0,1,0]
	v_cvt_pk_f16_f32 v20, v20, v21
	v_add_f32_dpp v130, v130, v130 quad_perm:[1,0,3,2] row_mask:0xf bank_mask:0xf bound_ctrl:1
	v_add_f32_dpp v131, v131, v131 quad_perm:[1,0,3,2] row_mask:0xf bank_mask:0xf bound_ctrl:1
	ds_write_b32 v47, v20 offset:12288
	ds_read_b128 v[24:27], v114 offset:15872
	ds_read_b128 v[20:23], v114 offset:19968
	ds_read_b128 v[28:31], v114 offset:11776
	ds_read_b128 v[16:19], v114 offset:3584
	s_waitcnt lgkmcnt(5)
	v_pk_fma_f32 v[92:93], v[120:121], v[90:91], v[92:93] op_sel_hi:[0,1,1]
	v_add_f32_dpp v130, v130, v130 quad_perm:[2,3,0,1] row_mask:0xf bank_mask:0xf bound_ctrl:1
	v_add_f32_dpp v131, v131, v131 quad_perm:[2,3,0,1] row_mask:0xf bank_mask:0xf bound_ctrl:1
	v_pk_fma_f32 v[94:95], v[120:121], v[90:91], v[94:95] op_sel:[1,0,0]
	v_add_f32_dpp v130, v130, v130 row_half_mirror row_mask:0xf bank_mask:0xf bound_ctrl:1
	v_add_f32_dpp v131, v131, v131 row_half_mirror row_mask:0xf bank_mask:0xf bound_ctrl:1
	v_pk_fma_f32 v[32:33], v[122:123], v[90:91], v[32:33] op_sel_hi:[0,1,1]
	v_pk_fma_f32 v[34:35], v[122:123], v[90:91], v[34:35] op_sel:[1,0,0]
	v_add_f32_dpp v130, v130, v130 row_mirror row_mask:0xf bank_mask:0xf bound_ctrl:1
	v_add_f32_dpp v131, v131, v131 row_mirror row_mask:0xf bank_mask:0xf bound_ctrl:1
	v_pk_fma_f32 v[92:93], v[116:117], v[130:131], v[92:93] op_sel_hi:[0,1,1]
	v_pk_fma_f32 v[94:95], v[116:117], v[130:131], v[94:95] op_sel:[1,0,0]
	v_pk_fma_f32 v[32:33], v[118:119], v[130:131], v[32:33] op_sel_hi:[0,1,1]
	v_pk_fma_f32 v[34:35], v[118:119], v[130:131], v[34:35] op_sel:[1,0,0]
	ds_read_b64 v[96:97], v115 offset:22272
	v_pk_mul_f32 v[12:13], v[92:93], v[124:125] op_sel_hi:[1,0]
	v_pk_fma_f32 v[12:13], v[94:95], v[124:125], v[12:13] op_sel:[0,1,0]
	v_pk_fma_f32 v[12:13], v[32:33], v[126:127], v[12:13] op_sel_hi:[1,0,1]
	v_pk_fma_f32 v[12:13], v[34:35], v[126:127], v[12:13] op_sel:[0,1,0]
	v_cvt_pk_f16_f32 v12, v12, v13
	ds_write_b32 v47, v12 offset:13312
	s_waitcnt lgkmcnt(0)
	v_pk_mul_f32 v[130:131], v[92:93], v[24:25] op_sel_hi:[1,0]
	v_pk_fma_f32 v[130:131], v[94:95], v[24:25], v[130:131] op_sel:[0,1,0]
	v_pk_fma_f32 v[130:131], v[32:33], v[26:27], v[130:131] op_sel_hi:[1,0,1]
	v_pk_fma_f32 v[130:131], v[34:35], v[26:27], v[130:131] op_sel:[0,1,0]
	v_pk_fma_f32 v[92:93], v[28:29], v[96:97], v[92:93] op_sel_hi:[0,1,1]
	v_pk_fma_f32 v[94:95], v[28:29], v[96:97], v[94:95] op_sel:[1,0,0]
	v_add_f32_dpp v130, v130, v130 quad_perm:[1,0,3,2] row_mask:0xf bank_mask:0xf bound_ctrl:1
	v_add_f32_dpp v131, v131, v131 quad_perm:[1,0,3,2] row_mask:0xf bank_mask:0xf bound_ctrl:1
	v_pk_fma_f32 v[32:33], v[30:31], v[96:97], v[32:33] op_sel_hi:[0,1,1]
	v_add_f32_dpp v130, v130, v130 quad_perm:[2,3,0,1] row_mask:0xf bank_mask:0xf bound_ctrl:1
	v_add_f32_dpp v131, v131, v131 quad_perm:[2,3,0,1] row_mask:0xf bank_mask:0xf bound_ctrl:1
	v_pk_fma_f32 v[34:35], v[30:31], v[96:97], v[34:35] op_sel:[1,0,0]
	v_add_f32_dpp v130, v130, v130 row_half_mirror row_mask:0xf bank_mask:0xf bound_ctrl:1
	v_add_f32_dpp v131, v131, v131 row_half_mirror row_mask:0xf bank_mask:0xf bound_ctrl:1
	ds_read_b128 v[12:15], v113 offset:15872
	ds_read_b128 v[116:119], v113 offset:19968
	ds_read_b128 v[120:123], v113 offset:11776
	ds_read_b128 v[124:127], v113 offset:3584
	ds_read_b64 v[90:91], v112 offset:1792
	v_add_f32_dpp v130, v130, v130 row_mirror row_mask:0xf bank_mask:0xf bound_ctrl:1
	v_add_f32_dpp v131, v131, v131 row_mirror row_mask:0xf bank_mask:0xf bound_ctrl:1
	v_pk_fma_f32 v[92:93], v[20:21], v[130:131], v[92:93] op_sel_hi:[0,1,1]
	v_pk_fma_f32 v[94:95], v[20:21], v[130:131], v[94:95] op_sel:[1,0,0]
	v_pk_fma_f32 v[32:33], v[22:23], v[130:131], v[32:33] op_sel_hi:[0,1,1]
	v_pk_fma_f32 v[34:35], v[22:23], v[130:131], v[34:35] op_sel:[1,0,0]
	s_waitcnt lgkmcnt(4)
	v_pk_mul_f32 v[130:131], v[92:93], v[12:13] op_sel_hi:[1,0]
	v_pk_mul_f32 v[20:21], v[92:93], v[16:17] op_sel_hi:[1,0]
	v_pk_fma_f32 v[130:131], v[94:95], v[12:13], v[130:131] op_sel:[0,1,0]
	v_pk_fma_f32 v[20:21], v[94:95], v[16:17], v[20:21] op_sel:[0,1,0]
	v_pk_fma_f32 v[130:131], v[32:33], v[14:15], v[130:131] op_sel_hi:[1,0,1]
	v_pk_fma_f32 v[20:21], v[32:33], v[18:19], v[20:21] op_sel_hi:[1,0,1]
	v_pk_fma_f32 v[130:131], v[34:35], v[14:15], v[130:131] op_sel:[0,1,0]
	v_pk_fma_f32 v[20:21], v[34:35], v[18:19], v[20:21] op_sel:[0,1,0]
	v_cvt_pk_f16_f32 v20, v20, v21
	v_add_f32_dpp v130, v130, v130 quad_perm:[1,0,3,2] row_mask:0xf bank_mask:0xf bound_ctrl:1
	v_add_f32_dpp v131, v131, v131 quad_perm:[1,0,3,2] row_mask:0xf bank_mask:0xf bound_ctrl:1
	ds_write_b32 v47, v20 offset:14336
	ds_read_b128 v[24:27], v114 offset:15872
	ds_read_b128 v[20:23], v114 offset:19968
	ds_read_b128 v[28:31], v114 offset:11776
	ds_read_b128 v[16:19], v114 offset:3584
	s_waitcnt lgkmcnt(5)
	v_pk_fma_f32 v[92:93], v[120:121], v[90:91], v[92:93] op_sel_hi:[0,1,1]
	v_add_f32_dpp v130, v130, v130 quad_perm:[2,3,0,1] row_mask:0xf bank_mask:0xf bound_ctrl:1
	v_add_f32_dpp v131, v131, v131 quad_perm:[2,3,0,1] row_mask:0xf bank_mask:0xf bound_ctrl:1
	v_pk_fma_f32 v[94:95], v[120:121], v[90:91], v[94:95] op_sel:[1,0,0]
	v_add_f32_dpp v130, v130, v130 row_half_mirror row_mask:0xf bank_mask:0xf bound_ctrl:1
	v_add_f32_dpp v131, v131, v131 row_half_mirror row_mask:0xf bank_mask:0xf bound_ctrl:1
	v_pk_fma_f32 v[32:33], v[122:123], v[90:91], v[32:33] op_sel_hi:[0,1,1]
	v_pk_fma_f32 v[34:35], v[122:123], v[90:91], v[34:35] op_sel:[1,0,0]
	v_add_f32_dpp v130, v130, v130 row_mirror row_mask:0xf bank_mask:0xf bound_ctrl:1
	v_add_f32_dpp v131, v131, v131 row_mirror row_mask:0xf bank_mask:0xf bound_ctrl:1
	v_pk_fma_f32 v[92:93], v[116:117], v[130:131], v[92:93] op_sel_hi:[0,1,1]
	v_pk_fma_f32 v[94:95], v[116:117], v[130:131], v[94:95] op_sel:[1,0,0]
	v_pk_fma_f32 v[32:33], v[118:119], v[130:131], v[32:33] op_sel_hi:[0,1,1]
	v_pk_fma_f32 v[34:35], v[118:119], v[130:131], v[34:35] op_sel:[1,0,0]
	ds_read_b64 v[96:97], v115 offset:22272
	v_pk_mul_f32 v[12:13], v[92:93], v[124:125] op_sel_hi:[1,0]
	v_pk_fma_f32 v[12:13], v[94:95], v[124:125], v[12:13] op_sel:[0,1,0]
	v_pk_fma_f32 v[12:13], v[32:33], v[126:127], v[12:13] op_sel_hi:[1,0,1]
	v_pk_fma_f32 v[12:13], v[34:35], v[126:127], v[12:13] op_sel:[0,1,0]
	v_cvt_pk_f16_f32 v12, v12, v13
	ds_write_b32 v47, v12 offset:15360
	v_swap_b32 v93, v94
	v_swap_b32 v33, v34
	ds_read_b128 v[12:15], v114 offset:7936
	s_add_i32 s93, s93, 3
	s_and_b64 vcc, exec, s[82:83]
	s_cbranch_vccz .LBB0_409
	s_waitcnt lgkmcnt(4)
	v_cvt_f32_f16_sdwa v29, v50 dst_sel:DWORD dst_unused:UNUSED_PAD src0_sel:WORD_1
	v_cvt_f32_f16_e32 v28, v50
	v_cvt_f32_f16_sdwa v31, v51 dst_sel:DWORD dst_unused:UNUSED_PAD src0_sel:WORD_1
	v_cvt_f32_f16_e32 v30, v51
	s_waitcnt lgkmcnt(3)
	v_cvt_f32_f16_sdwa v17, v56 dst_sel:DWORD dst_unused:UNUSED_PAD src0_sel:WORD_1
	v_cvt_f32_f16_e32 v16, v56
	v_cvt_f32_f16_sdwa v19, v57 dst_sel:DWORD dst_unused:UNUSED_PAD src0_sel:WORD_1
	v_cvt_f32_f16_e32 v18, v57
	v_pk_mul_f32 v[22:23], v[0:1], v[28:29]
	v_pk_mul_f32 v[20:21], v[2:3], v[30:31]
	s_waitcnt lgkmcnt(2)
	v_pk_mul_f32 v[96:97], v[22:23], v[22:23]
	v_pk_mul_f32 v[90:91], v[20:21], v[20:21]
	v_add_f32_e32 v42, v96, v97
	v_cvt_f32_f16_sdwa v25, v48 dst_sel:DWORD dst_unused:UNUSED_PAD src0_sel:WORD_1
	v_cvt_f32_f16_e32 v24, v48
	v_cvt_f32_f16_sdwa v27, v49 dst_sel:DWORD dst_unused:UNUSED_PAD src0_sel:WORD_1
	v_cvt_f32_f16_e32 v26, v49
	v_add_f32_e32 v42, v90, v42
	v_add_f32_e32 v42, v91, v42
	v_pk_add_f32 v[90:91], v[16:17], -1.0 op_sel_hi:[1,0]
	v_pk_add_f32 v[96:97], v[18:19], -1.0 op_sel_hi:[1,0]
	v_pk_fma_f32 v[90:91], v[4:5], v[90:91], 1.0 op_sel_hi:[1,1,0]
	v_pk_fma_f32 v[96:97], v[6:7], v[96:97], 1.0 op_sel_hi:[1,1,0]
	v_pk_mul_f32 v[90:91], v[28:29], v[90:91]
	v_pk_mul_f32 v[96:97], v[30:31], v[96:97]
	v_pk_mul_f32 v[28:29], v[24:25], v[90:91]
	v_pk_mul_f32 v[30:31], v[26:27], v[96:97]
	v_pk_mul_f32 v[28:29], v[8:9], v[28:29]
	v_pk_mul_f32 v[30:31], v[10:11], v[30:31]
	v_add_f32_e32 v28, v28, v29
	v_add_f32_e32 v29, v30, v31
	v_add_f32_e32 v28, v28, v29
	v_add_f32_dpp v42, v42, v42 quad_perm:[1,0,3,2] row_mask:0xf bank_mask:0xf bound_ctrl:1
	s_nop 0
	v_add_f32_dpp v28, v28, v28 quad_perm:[1,0,3,2] row_mask:0xf bank_mask:0xf bound_ctrl:1
	v_add_f32_dpp v42, v42, v42 quad_perm:[2,3,0,1] row_mask:0xf bank_mask:0xf bound_ctrl:1
	s_nop 0
	v_add_f32_dpp v28, v28, v28 quad_perm:[2,3,0,1] row_mask:0xf bank_mask:0xf bound_ctrl:1
	v_add_f32_dpp v42, v42, v42 row_half_mirror row_mask:0xf bank_mask:0xf bound_ctrl:1
	s_nop 0
	v_add_f32_dpp v28, v28, v28 row_half_mirror row_mask:0xf bank_mask:0xf bound_ctrl:1
	v_mov_b32_dpp v47, v42 row_mirror row_mask:0xf bank_mask:0xf bound_ctrl:1
	s_nop 0
	v_mov_b32_dpp v29, v28 row_mirror row_mask:0xf bank_mask:0xf bound_ctrl:1
	s_and_saveexec_b64 s[12:13], s[6:7]
	s_cbranch_execz .LBB0_442
	s_add_i32 s94, s94, 48
	v_cmp_lt_u32_e32 vcc, s94, v106
	s_and_b64 exec, exec, vcc
	s_cbranch_execz .LBB0_442
	v_add_f32_e32 v30, v28, v29
	v_add_u32_e32 v28, s94, v46
	v_ashrrev_i32_e32 v29, 31, v28
	v_lshlrev_b64 v[28:29], 6, v[28:29]
	v_lshl_add_u64 v[28:29], s[58:59], 0, v[28:29]
	global_store_dword v[28:29], v30, off
